# P0 silu(c) staging de-serialised (16 loads in flight); P1 position loads hoisted and issued together, rows 0-1 of each wave prefetched during the rope/mod prologue, 4-row loop unrolled
# speedup vs baseline: 1.0107x; 1.0107x over previous
.LBB0_19:
	v_mov_b32_e32 v0, v252
	s_movk_i32 s0, 0x2000
	s_nop 0
	v_cmp_gt_i32_e32 vcc, s0, v0
	s_and_saveexec_b64 s[4:5], vcc
	s_cbranch_execz .LBB0_22
	v_lshlrev_b32_e32 v5, 2, v0
	s_mov_b32 s6, s18
	s_mov_b32 s7, s19
	global_load_dword v14, v5, s[6:7]
	global_load_dword v15, v5, s[6:7] offset:2048
	s_add_u32 s6, s6, 0x1000
	s_addc_u32 s7, s7, 0
	global_load_dword v16, v5, s[6:7]
	global_load_dword v17, v5, s[6:7] offset:2048
	s_add_u32 s6, s6, 0x1000
	s_addc_u32 s7, s7, 0
	global_load_dword v18, v5, s[6:7]
	global_load_dword v19, v5, s[6:7] offset:2048
	s_add_u32 s6, s6, 0x1000
	s_addc_u32 s7, s7, 0
	global_load_dword v20, v5, s[6:7]
	global_load_dword v21, v5, s[6:7] offset:2048
	s_add_u32 s6, s6, 0x1000
	s_addc_u32 s7, s7, 0
	global_load_dword v22, v5, s[6:7]
	global_load_dword v23, v5, s[6:7] offset:2048
	s_add_u32 s6, s6, 0x1000
	s_addc_u32 s7, s7, 0
	global_load_dword v24, v5, s[6:7]
	global_load_dword v25, v5, s[6:7] offset:2048
	s_add_u32 s6, s6, 0x1000
	s_addc_u32 s7, s7, 0
	global_load_dword v26, v5, s[6:7]
	global_load_dword v27, v5, s[6:7] offset:2048
	s_add_u32 s6, s6, 0x1000
	s_addc_u32 s7, s7, 0
	global_load_dword v28, v5, s[6:7]
	global_load_dword v29, v5, s[6:7] offset:2048
	s_waitcnt vmcnt(15)
	v_mul_f32_e32 v6, 0xbfb8aa3b, v14
	v_exp_f32_e32 v6, v6
	s_nop 0
	v_add_f32_e32 v6, 1.0, v6
	v_div_scale_f32 v7, s[10:11], v6, v6, v14
	v_rcp_f32_e32 v8, v7
	v_div_scale_f32 v9, vcc, v14, v6, v14
	v_fma_f32 v10, -v7, v8, 1.0
	v_fmac_f32_e32 v8, v10, v8
	v_mul_f32_e32 v10, v9, v8
	v_fma_f32 v11, -v7, v10, v9
	v_fmac_f32_e32 v10, v11, v8
	v_fma_f32 v7, -v7, v10, v9
	v_div_fmas_f32 v7, v7, v8, v10
	v_div_fixup_f32 v1, v7, v6, v14
	ds_write_b32 v5, v1 offset:0
	s_waitcnt vmcnt(14)
	v_mul_f32_e32 v6, 0xbfb8aa3b, v15
	v_exp_f32_e32 v6, v6
	s_nop 0
	v_add_f32_e32 v6, 1.0, v6
	v_div_scale_f32 v7, s[10:11], v6, v6, v15
	v_rcp_f32_e32 v8, v7
	v_div_scale_f32 v9, vcc, v15, v6, v15
	v_fma_f32 v10, -v7, v8, 1.0
	v_fmac_f32_e32 v8, v10, v8
	v_mul_f32_e32 v10, v9, v8
	v_fma_f32 v11, -v7, v10, v9
	v_fmac_f32_e32 v10, v11, v8
	v_fma_f32 v7, -v7, v10, v9
	v_div_fmas_f32 v7, v7, v8, v10
	v_div_fixup_f32 v1, v7, v6, v15
	ds_write_b32 v5, v1 offset:2048
	s_waitcnt vmcnt(13)
	v_mul_f32_e32 v6, 0xbfb8aa3b, v16
	v_exp_f32_e32 v6, v6
	s_nop 0
	v_add_f32_e32 v6, 1.0, v6
	v_div_scale_f32 v7, s[10:11], v6, v6, v16
	v_rcp_f32_e32 v8, v7
	v_div_scale_f32 v9, vcc, v16, v6, v16
	v_fma_f32 v10, -v7, v8, 1.0
	v_fmac_f32_e32 v8, v10, v8
	v_mul_f32_e32 v10, v9, v8
	v_fma_f32 v11, -v7, v10, v9
	v_fmac_f32_e32 v10, v11, v8
	v_fma_f32 v7, -v7, v10, v9
	v_div_fmas_f32 v7, v7, v8, v10
	v_div_fixup_f32 v1, v7, v6, v16
	ds_write_b32 v5, v1 offset:4096
	s_waitcnt vmcnt(12)
	v_mul_f32_e32 v6, 0xbfb8aa3b, v17
	v_exp_f32_e32 v6, v6
	s_nop 0
	v_add_f32_e32 v6, 1.0, v6
	v_div_scale_f32 v7, s[10:11], v6, v6, v17
	v_rcp_f32_e32 v8, v7
	v_div_scale_f32 v9, vcc, v17, v6, v17
	v_fma_f32 v10, -v7, v8, 1.0
	v_fmac_f32_e32 v8, v10, v8
	v_mul_f32_e32 v10, v9, v8
	v_fma_f32 v11, -v7, v10, v9
	v_fmac_f32_e32 v10, v11, v8
	v_fma_f32 v7, -v7, v10, v9
	v_div_fmas_f32 v7, v7, v8, v10
	v_div_fixup_f32 v1, v7, v6, v17
	ds_write_b32 v5, v1 offset:6144
	s_waitcnt vmcnt(11)
	v_mul_f32_e32 v6, 0xbfb8aa3b, v18
	v_exp_f32_e32 v6, v6
	s_nop 0
	v_add_f32_e32 v6, 1.0, v6
	v_div_scale_f32 v7, s[10:11], v6, v6, v18
	v_rcp_f32_e32 v8, v7
	v_div_scale_f32 v9, vcc, v18, v6, v18
	v_fma_f32 v10, -v7, v8, 1.0
	v_fmac_f32_e32 v8, v10, v8
	v_mul_f32_e32 v10, v9, v8
	v_fma_f32 v11, -v7, v10, v9
	v_fmac_f32_e32 v10, v11, v8
	v_fma_f32 v7, -v7, v10, v9
	v_div_fmas_f32 v7, v7, v8, v10
	v_div_fixup_f32 v1, v7, v6, v18
	ds_write_b32 v5, v1 offset:8192
	s_waitcnt vmcnt(10)
	v_mul_f32_e32 v6, 0xbfb8aa3b, v19
	v_exp_f32_e32 v6, v6
	s_nop 0
	v_add_f32_e32 v6, 1.0, v6
	v_div_scale_f32 v7, s[10:11], v6, v6, v19
	v_rcp_f32_e32 v8, v7
	v_div_scale_f32 v9, vcc, v19, v6, v19
	v_fma_f32 v10, -v7, v8, 1.0
	v_fmac_f32_e32 v8, v10, v8
	v_mul_f32_e32 v10, v9, v8
	v_fma_f32 v11, -v7, v10, v9
	v_fmac_f32_e32 v10, v11, v8
	v_fma_f32 v7, -v7, v10, v9
	v_div_fmas_f32 v7, v7, v8, v10
	v_div_fixup_f32 v1, v7, v6, v19
	ds_write_b32 v5, v1 offset:10240
	s_waitcnt vmcnt(9)
	v_mul_f32_e32 v6, 0xbfb8aa3b, v20
	v_exp_f32_e32 v6, v6
	s_nop 0
	v_add_f32_e32 v6, 1.0, v6
	v_div_scale_f32 v7, s[10:11], v6, v6, v20
	v_rcp_f32_e32 v8, v7
	v_div_scale_f32 v9, vcc, v20, v6, v20
	v_fma_f32 v10, -v7, v8, 1.0
	v_fmac_f32_e32 v8, v10, v8
	v_mul_f32_e32 v10, v9, v8
	v_fma_f32 v11, -v7, v10, v9
	v_fmac_f32_e32 v10, v11, v8
	v_fma_f32 v7, -v7, v10, v9
	v_div_fmas_f32 v7, v7, v8, v10
	v_div_fixup_f32 v1, v7, v6, v20
	ds_write_b32 v5, v1 offset:12288
	s_waitcnt vmcnt(8)
	v_mul_f32_e32 v6, 0xbfb8aa3b, v21
	v_exp_f32_e32 v6, v6
	s_nop 0
	v_add_f32_e32 v6, 1.0, v6
	v_div_scale_f32 v7, s[10:11], v6, v6, v21
	v_rcp_f32_e32 v8, v7
	v_div_scale_f32 v9, vcc, v21, v6, v21
	v_fma_f32 v10, -v7, v8, 1.0
	v_fmac_f32_e32 v8, v10, v8
	v_mul_f32_e32 v10, v9, v8
	v_fma_f32 v11, -v7, v10, v9
	v_fmac_f32_e32 v10, v11, v8
	v_fma_f32 v7, -v7, v10, v9
	v_div_fmas_f32 v7, v7, v8, v10
	v_div_fixup_f32 v1, v7, v6, v21
	ds_write_b32 v5, v1 offset:14336
	s_waitcnt vmcnt(7)
	v_mul_f32_e32 v6, 0xbfb8aa3b, v22
	v_exp_f32_e32 v6, v6
	s_nop 0
	v_add_f32_e32 v6, 1.0, v6
	v_div_scale_f32 v7, s[10:11], v6, v6, v22
	v_rcp_f32_e32 v8, v7
	v_div_scale_f32 v9, vcc, v22, v6, v22
	v_fma_f32 v10, -v7, v8, 1.0
	v_fmac_f32_e32 v8, v10, v8
	v_mul_f32_e32 v10, v9, v8
	v_fma_f32 v11, -v7, v10, v9
	v_fmac_f32_e32 v10, v11, v8
	v_fma_f32 v7, -v7, v10, v9
	v_div_fmas_f32 v7, v7, v8, v10
	v_div_fixup_f32 v1, v7, v6, v22
	ds_write_b32 v5, v1 offset:16384
	s_waitcnt vmcnt(6)
	v_mul_f32_e32 v6, 0xbfb8aa3b, v23
	v_exp_f32_e32 v6, v6
	s_nop 0
	v_add_f32_e32 v6, 1.0, v6
	v_div_scale_f32 v7, s[10:11], v6, v6, v23
	v_rcp_f32_e32 v8, v7
	v_div_scale_f32 v9, vcc, v23, v6, v23
	v_fma_f32 v10, -v7, v8, 1.0
	v_fmac_f32_e32 v8, v10, v8
	v_mul_f32_e32 v10, v9, v8
	v_fma_f32 v11, -v7, v10, v9
	v_fmac_f32_e32 v10, v11, v8
	v_fma_f32 v7, -v7, v10, v9
	v_div_fmas_f32 v7, v7, v8, v10
	v_div_fixup_f32 v1, v7, v6, v23
	ds_write_b32 v5, v1 offset:18432
	s_waitcnt vmcnt(5)
	v_mul_f32_e32 v6, 0xbfb8aa3b, v24
	v_exp_f32_e32 v6, v6
	s_nop 0
	v_add_f32_e32 v6, 1.0, v6
	v_div_scale_f32 v7, s[10:11], v6, v6, v24
	v_rcp_f32_e32 v8, v7
	v_div_scale_f32 v9, vcc, v24, v6, v24
	v_fma_f32 v10, -v7, v8, 1.0
	v_fmac_f32_e32 v8, v10, v8
	v_mul_f32_e32 v10, v9, v8
	v_fma_f32 v11, -v7, v10, v9
	v_fmac_f32_e32 v10, v11, v8
	v_fma_f32 v7, -v7, v10, v9
	v_div_fmas_f32 v7, v7, v8, v10
	v_div_fixup_f32 v1, v7, v6, v24
	ds_write_b32 v5, v1 offset:20480
	s_waitcnt vmcnt(4)
	v_mul_f32_e32 v6, 0xbfb8aa3b, v25
	v_exp_f32_e32 v6, v6
	s_nop 0
	v_add_f32_e32 v6, 1.0, v6
	v_div_scale_f32 v7, s[10:11], v6, v6, v25
	v_rcp_f32_e32 v8, v7
	v_div_scale_f32 v9, vcc, v25, v6, v25
	v_fma_f32 v10, -v7, v8, 1.0
	v_fmac_f32_e32 v8, v10, v8
	v_mul_f32_e32 v10, v9, v8
	v_fma_f32 v11, -v7, v10, v9
	v_fmac_f32_e32 v10, v11, v8
	v_fma_f32 v7, -v7, v10, v9
	v_div_fmas_f32 v7, v7, v8, v10
	v_div_fixup_f32 v1, v7, v6, v25
	ds_write_b32 v5, v1 offset:22528
	s_waitcnt vmcnt(3)
	v_mul_f32_e32 v6, 0xbfb8aa3b, v26
	v_exp_f32_e32 v6, v6
	s_nop 0
	v_add_f32_e32 v6, 1.0, v6
	v_div_scale_f32 v7, s[10:11], v6, v6, v26
	v_rcp_f32_e32 v8, v7
	v_div_scale_f32 v9, vcc, v26, v6, v26
	v_fma_f32 v10, -v7, v8, 1.0
	v_fmac_f32_e32 v8, v10, v8
	v_mul_f32_e32 v10, v9, v8
	v_fma_f32 v11, -v7, v10, v9
	v_fmac_f32_e32 v10, v11, v8
	v_fma_f32 v7, -v7, v10, v9
	v_div_fmas_f32 v7, v7, v8, v10
	v_div_fixup_f32 v1, v7, v6, v26
	ds_write_b32 v5, v1 offset:24576
	s_waitcnt vmcnt(2)
	v_mul_f32_e32 v6, 0xbfb8aa3b, v27
	v_exp_f32_e32 v6, v6
	s_nop 0
	v_add_f32_e32 v6, 1.0, v6
	v_div_scale_f32 v7, s[10:11], v6, v6, v27
	v_rcp_f32_e32 v8, v7
	v_div_scale_f32 v9, vcc, v27, v6, v27
	v_fma_f32 v10, -v7, v8, 1.0
	v_fmac_f32_e32 v8, v10, v8
	v_mul_f32_e32 v10, v9, v8
	v_fma_f32 v11, -v7, v10, v9
	v_fmac_f32_e32 v10, v11, v8
	v_fma_f32 v7, -v7, v10, v9
	v_div_fmas_f32 v7, v7, v8, v10
	v_div_fixup_f32 v1, v7, v6, v27
	ds_write_b32 v5, v1 offset:26624
	s_waitcnt vmcnt(1)
	v_mul_f32_e32 v6, 0xbfb8aa3b, v28
	v_exp_f32_e32 v6, v6
	s_nop 0
	v_add_f32_e32 v6, 1.0, v6
	v_div_scale_f32 v7, s[10:11], v6, v6, v28
	v_rcp_f32_e32 v8, v7
	v_div_scale_f32 v9, vcc, v28, v6, v28
	v_fma_f32 v10, -v7, v8, 1.0
	v_fmac_f32_e32 v8, v10, v8
	v_mul_f32_e32 v10, v9, v8
	v_fma_f32 v11, -v7, v10, v9
	v_fmac_f32_e32 v10, v11, v8
	v_fma_f32 v7, -v7, v10, v9
	v_div_fmas_f32 v7, v7, v8, v10
	v_div_fixup_f32 v1, v7, v6, v28
	ds_write_b32 v5, v1 offset:28672
	s_waitcnt vmcnt(0)
	v_mul_f32_e32 v6, 0xbfb8aa3b, v29
	v_exp_f32_e32 v6, v6
	s_nop 0
	v_add_f32_e32 v6, 1.0, v6
	v_div_scale_f32 v7, s[10:11], v6, v6, v29
	v_rcp_f32_e32 v8, v7
	v_div_scale_f32 v9, vcc, v29, v6, v29
	v_fma_f32 v10, -v7, v8, 1.0
	v_fmac_f32_e32 v8, v10, v8
	v_mul_f32_e32 v10, v9, v8
	v_fma_f32 v11, -v7, v10, v9
	v_fmac_f32_e32 v10, v11, v8
	v_fma_f32 v7, -v7, v10, v9
	v_div_fmas_f32 v7, v7, v8, v10
	v_div_fixup_f32 v1, v7, v6, v29
	ds_write_b32 v5, v1 offset:30720

.LBB0_97:
	s_lshl_b32 s49, s42, 5
	v_add_u32_e32 v0, s49, v120
	v_ashrrev_i32_e32 v1, 31, v0
	v_lshl_add_u64 v[0:1], v[0:1], 2, s[20:21]
	global_load_dword v0, v[0:1], off
	v_add_u32_e32 v244, s49, v121
	v_ashrrev_i32_e32 v245, 31, v244
	v_lshl_add_u64 v[244:245], v[244:245], 2, s[20:21]
	global_load_dword v240, v[244:245], off
	v_add_u32_e32 v244, s49, v122
	v_ashrrev_i32_e32 v245, 31, v244
	v_lshl_add_u64 v[244:245], v[244:245], 2, s[20:21]
	global_load_dword v241, v[244:245], off
	v_add_u32_e32 v244, s49, v123
	v_ashrrev_i32_e32 v245, 31, v244
	v_lshl_add_u64 v[244:245], v[244:245], 2, s[20:21]
	global_load_dword v242, v[244:245], off
	v_lshlrev_b32_e32 v232, 13, v110
	v_mov_b32_e32 v233, 0
	v_lshl_add_u64 v[232:233], v[108:109], 0, v[232:233]
	global_load_dwordx4 v[172:175], v[232:233], off offset:-4096 nt
	global_load_dwordx4 v[168:171], v[232:233], off offset:-3072 nt
	global_load_dwordx4 v[176:179], v[232:233], off offset:-2048 nt
	global_load_dwordx4 v[180:183], v[232:233], off nt
	global_load_dwordx4 v[184:187], v[232:233], off offset:1024 nt
	global_load_dwordx4 v[188:191], v[232:233], off offset:-1024 nt
	global_load_dwordx4 v[192:195], v[232:233], off offset:3072 nt
	global_load_dwordx4 v[196:199], v[232:233], off offset:2048 nt
	v_lshl_add_u64 v[232:233], v[232:233], 0, s[22:23]
	global_load_dwordx4 v[204:207], v[232:233], off offset:-4096 nt
	global_load_dwordx4 v[200:203], v[232:233], off offset:-3072 nt
	global_load_dwordx4 v[208:211], v[232:233], off offset:-2048 nt
	global_load_dwordx4 v[212:215], v[232:233], off nt
	global_load_dwordx4 v[216:219], v[232:233], off offset:1024 nt
	global_load_dwordx4 v[220:223], v[232:233], off offset:-1024 nt
	global_load_dwordx4 v[224:227], v[232:233], off offset:3072 nt
	global_load_dwordx4 v[228:231], v[232:233], off offset:2048 nt
	v_lshl_add_u64 v[232:233], v[232:233], 0, s[22:23]
	s_waitcnt vmcnt(16)
	v_cvt_f32_i32_e32 v0, v0
	v_mul_f32_e32 v4, v118, v0
	v_and_b32_e32 v0, 0x7fffffff, v4
	v_cmp_nlt_f32_e64 s[0:1], |v4|, s33
	s_and_saveexec_b64 s[14:15], s[0:1]
	s_xor_b64 s[46:47], exec, s[14:15]
	s_cbranch_execz .LBB0_99
	v_lshrrev_b32_e32 v1, 23, v0
	v_add_u32_e32 v1, 0xffffff88, v1
	v_cmp_lt_u32_e32 vcc, 63, v1
	s_nop 1
	v_cndmask_b32_e32 v2, 0, v132, vcc
	v_add_u32_e32 v1, v2, v1
	v_cmp_lt_u32_e64 s[14:15], 31, v1
	s_nop 1
	v_cndmask_b32_e64 v2, 0, v133, s[14:15]
	v_add_u32_e32 v1, v2, v1
	v_cmp_lt_u32_e64 s[16:17], 31, v1
	s_nop 1
	v_cndmask_b32_e64 v2, 0, v133, s[16:17]
	v_add_u32_e32 v1, v2, v1
	v_and_b32_e32 v2, 0x7fffff, v0
	v_or_b32_e32 v5, 0x800000, v2
	v_mad_u64_u32 v[2:3], s[0:1], v5, s38, 0
	v_mov_b32_e32 v100, v3
	v_mad_u64_u32 v[6:7], s[0:1], v5, s39, v[100:101]
	v_mov_b32_e32 v100, v7
	v_mad_u64_u32 v[8:9], s[0:1], v5, s68, v[100:101]
	v_mov_b32_e32 v100, v9
	v_mad_u64_u32 v[10:11], s[0:1], v5, s69, v[100:101]
	v_mov_b32_e32 v100, v11
	v_mad_u64_u32 v[12:13], s[0:1], v5, s70, v[100:101]
	v_mov_b32_e32 v100, v13
	v_mad_u64_u32 v[14:15], s[0:1], v5, s71, v[100:101]
	v_mov_b32_e32 v100, v15
	v_mad_u64_u32 v[16:17], s[0:1], v5, s72, v[100:101]
	v_cndmask_b32_e32 v3, v14, v10, vcc
	v_cndmask_b32_e32 v5, v16, v12, vcc
	v_cndmask_b32_e32 v9, v17, v14, vcc
	v_cndmask_b32_e64 v7, v5, v3, s[14:15]
	v_cndmask_b32_e64 v5, v9, v5, s[14:15]
	v_cndmask_b32_e32 v9, v12, v8, vcc
	v_cndmask_b32_e64 v3, v3, v9, s[14:15]
	v_cndmask_b32_e64 v5, v5, v7, s[16:17]
	v_cndmask_b32_e64 v7, v7, v3, s[16:17]
	v_sub_u32_e32 v11, 32, v1
	v_alignbit_b32 v12, v5, v7, v11
	v_cmp_eq_u32_e64 s[18:19], 0, v1
	v_cndmask_b32_e32 v2, v8, v2, vcc
	s_nop 0
	v_cndmask_b32_e64 v1, v12, v5, s[18:19]
	v_cndmask_b32_e32 v5, v10, v6, vcc
	v_cndmask_b32_e64 v6, v9, v5, s[14:15]
	v_cndmask_b32_e64 v3, v3, v6, s[16:17]
	v_alignbit_b32 v9, v7, v3, v11
	v_cndmask_b32_e64 v7, v9, v7, s[18:19]
	v_bfe_u32 v12, v1, 29, 1
	v_cndmask_b32_e64 v2, v5, v2, s[14:15]
	v_alignbit_b32 v9, v1, v7, 30
	v_sub_u32_e32 v13, 0, v12
	v_cndmask_b32_e64 v2, v6, v2, s[16:17]
	v_xor_b32_e32 v9, v9, v13
	v_alignbit_b32 v5, v3, v2, v11
	v_cndmask_b32_e64 v3, v5, v3, s[18:19]
	v_ffbh_u32_e32 v6, v9
	v_alignbit_b32 v5, v7, v3, 30
	v_min_u32_e32 v6, 32, v6
	v_alignbit_b32 v2, v3, v2, 30
	v_xor_b32_e32 v5, v5, v13
	v_sub_u32_e32 v7, 31, v6
	v_xor_b32_e32 v2, v2, v13
	v_alignbit_b32 v8, v9, v5, v7
	v_alignbit_b32 v2, v5, v2, v7
	v_alignbit_b32 v3, v8, v2, 9
	v_ffbh_u32_e32 v5, v3
	v_min_u32_e32 v5, 32, v5
	v_lshrrev_b32_e32 v10, 29, v1
	v_not_b32_e32 v7, v5
	v_alignbit_b32 v2, v3, v2, v7
	v_lshlrev_b32_e32 v3, 31, v10
	v_or_b32_e32 v7, 0x33000000, v3
	v_add_lshl_u32 v5, v5, v6, 23
	v_lshrrev_b32_e32 v2, 9, v2
	v_sub_u32_e32 v5, v7, v5
	v_or_b32_e32 v3, 0.5, v3
	v_lshlrev_b32_e32 v6, 23, v6
	v_or_b32_e32 v2, v5, v2
	v_lshrrev_b32_e32 v5, 9, v8
	v_sub_u32_e32 v3, v3, v6
	v_or_b32_e32 v3, v5, v3
	v_mul_f32_e32 v5, 0x3fc90fda, v3
	v_fma_f32 v6, v3, s73, -v5
	v_fmac_f32_e32 v6, 0x33a22168, v3
	v_fmac_f32_e32 v6, 0x3fc90fda, v2
	v_lshrrev_b32_e32 v1, 30, v1
	v_add_f32_e32 v5, v5, v6
	v_add_u32_e32 v1, v12, v1
.LBB0_99:
	s_andn2_saveexec_b64 s[14:15], s[46:47]
	v_mul_f32_e64 v1, |v4|, s74
	v_rndne_f32_e32 v2, v1
	v_cvt_i32_f32_e32 v1, v2
	v_fma_f32 v5, v2, s75, |v4|
	v_fmac_f32_e32 v5, 0xb3a22168, v2
	v_fmac_f32_e32 v5, 0xa7c234c4, v2
	s_or_b64 exec, exec, s[14:15]
	v_add_u32_e32 v2, s49, v121
	v_ashrrev_i32_e32 v3, 31, v2
	v_lshl_add_u64 v[2:3], v[2:3], 2, s[20:21]
	v_mov_b32_e32 v6, v240
	v_mul_f32_e32 v7, v5, v5
	v_lshlrev_b32_e32 v8, 30, v1
	v_and_b32_e32 v9, 1, v1
	v_xor_b32_e32 v10, v0, v4
	v_fmamk_f32 v0, v7, 0xb94c1982, v128
	v_fmamk_f32 v1, v7, 0x37d75334, v129
	v_fmaak_f32 v12, v7, v0, 0xbe2aaa9d
	v_fmaak_f32 v13, v7, v1, 0x3d2aabf7
	v_mul_f32_e32 v12, v7, v12
	v_fmaak_f32 v13, v7, v13, 0xbf000004
	v_fmac_f32_e32 v5, v5, v12
	v_fma_f32 v7, v7, v13, 1.0
	v_cmp_eq_u32_e32 vcc, 0, v9
	s_ashr_i32 s43, s42, 31
	v_and_b32_e32 v11, 0x80000000, v8
	v_cndmask_b32_e32 v9, v7, v5, vcc
	v_xor_b32_e32 v5, 0x80000000, v5
	v_cndmask_b32_e32 v5, v5, v7, vcc
	v_bitop3_b32 v5, v5, v8, s78 bitop3:0x78
	v_cmp_class_f32_e64 vcc, v4, s79
	s_lshl_b64 s[0:1], s[42:43], 13
	v_xor_b32_e32 v9, v10, v9
	v_cndmask_b32_e32 v4, v134, v5, vcc
	v_lshl_add_u64 v[2:3], v[104:105], 0, s[0:1]
	v_xor_b32_e32 v7, v9, v11
	v_lshl_add_u64 v[0:1], v[106:107], 0, s[0:1]
	v_cvt_f32_i32_e32 v5, v6
	v_cndmask_b32_e32 v6, v134, v7, vcc
	global_store_dword v[2:3], v4, off
	global_store_dword v[0:1], v6, off
	v_mul_f32_e32 v4, v118, v5
	v_and_b32_e32 v5, 0x7fffffff, v4
	v_cmp_nlt_f32_e64 s[0:1], |v4|, s33
	s_and_saveexec_b64 s[14:15], s[0:1]
	s_xor_b64 s[46:47], exec, s[14:15]
	s_cbranch_execz .LBB0_103
	v_lshrrev_b32_e32 v6, 23, v5
	v_add_u32_e32 v6, 0xffffff88, v6
	v_cmp_lt_u32_e32 vcc, 63, v6
	s_nop 1
	v_cndmask_b32_e32 v7, 0, v132, vcc
	v_add_u32_e32 v6, v7, v6
	v_cmp_lt_u32_e64 s[14:15], 31, v6
	s_nop 1
	v_cndmask_b32_e64 v7, 0, v133, s[14:15]
	v_add_u32_e32 v6, v7, v6
	v_cmp_lt_u32_e64 s[16:17], 31, v6
	s_nop 1
	v_cndmask_b32_e64 v7, 0, v133, s[16:17]
	v_add_u32_e32 v20, v7, v6
	v_and_b32_e32 v6, 0x7fffff, v5
	v_or_b32_e32 v18, 0x800000, v6
	v_mad_u64_u32 v[6:7], s[0:1], v18, s38, 0
	v_mov_b32_e32 v100, v7
	v_mad_u64_u32 v[8:9], s[0:1], v18, s39, v[100:101]
	v_mov_b32_e32 v100, v9
	v_mad_u64_u32 v[10:11], s[0:1], v18, s68, v[100:101]
	v_mov_b32_e32 v100, v11
	v_mad_u64_u32 v[12:13], s[0:1], v18, s69, v[100:101]
	v_mov_b32_e32 v100, v13
	v_mad_u64_u32 v[14:15], s[0:1], v18, s70, v[100:101]
	v_mov_b32_e32 v100, v15
	v_mad_u64_u32 v[16:17], s[0:1], v18, s71, v[100:101]
	v_mov_b32_e32 v100, v17
	v_mad_u64_u32 v[18:19], s[0:1], v18, s72, v[100:101]
	v_cndmask_b32_e32 v7, v16, v12, vcc
	v_cndmask_b32_e32 v9, v18, v14, vcc
	v_cndmask_b32_e32 v13, v19, v16, vcc
	v_cndmask_b32_e64 v11, v9, v7, s[14:15]
	v_cndmask_b32_e64 v9, v13, v9, s[14:15]
	v_cndmask_b32_e32 v13, v14, v10, vcc
	v_cndmask_b32_e64 v7, v7, v13, s[14:15]
	v_cndmask_b32_e32 v8, v12, v8, vcc
	v_cndmask_b32_e64 v9, v9, v11, s[16:17]
	v_cndmask_b32_e64 v11, v11, v7, s[16:17]
	v_sub_u32_e32 v14, 32, v20
	v_cndmask_b32_e64 v12, v13, v8, s[14:15]
	v_alignbit_b32 v15, v9, v11, v14
	v_cmp_eq_u32_e64 s[18:19], 0, v20
	v_cndmask_b32_e64 v7, v7, v12, s[16:17]
	v_alignbit_b32 v13, v11, v7, v14
	v_cndmask_b32_e64 v9, v15, v9, s[18:19]
	v_cndmask_b32_e32 v6, v10, v6, vcc
	v_cndmask_b32_e64 v11, v13, v11, s[18:19]
	v_bfe_u32 v16, v9, 29, 1
	v_cndmask_b32_e64 v6, v8, v6, s[14:15]
	v_alignbit_b32 v13, v9, v11, 30
	v_sub_u32_e32 v17, 0, v16
	v_cndmask_b32_e64 v6, v12, v6, s[16:17]
	v_xor_b32_e32 v13, v13, v17
	v_alignbit_b32 v8, v7, v6, v14
	v_cndmask_b32_e64 v7, v8, v7, s[18:19]
	v_ffbh_u32_e32 v10, v13
	v_alignbit_b32 v8, v11, v7, 30
	v_min_u32_e32 v10, 32, v10
	v_alignbit_b32 v6, v7, v6, 30
	v_xor_b32_e32 v8, v8, v17
	v_sub_u32_e32 v11, 31, v10
	v_xor_b32_e32 v6, v6, v17
	v_alignbit_b32 v12, v13, v8, v11
	v_alignbit_b32 v6, v8, v6, v11
	v_alignbit_b32 v7, v12, v6, 9
	v_ffbh_u32_e32 v8, v7
	v_min_u32_e32 v8, 32, v8
	v_lshrrev_b32_e32 v15, 29, v9
	v_not_b32_e32 v11, v8
	v_alignbit_b32 v6, v7, v6, v11
	v_lshlrev_b32_e32 v7, 31, v15
	v_or_b32_e32 v11, 0x33000000, v7
	v_add_lshl_u32 v8, v8, v10, 23
	v_lshrrev_b32_e32 v6, 9, v6
	v_sub_u32_e32 v8, v11, v8
	v_or_b32_e32 v7, 0.5, v7
	v_lshlrev_b32_e32 v10, 23, v10
	v_or_b32_e32 v6, v8, v6
	v_lshrrev_b32_e32 v8, 9, v12
	v_sub_u32_e32 v7, v7, v10
	v_or_b32_e32 v7, v8, v7
	v_mul_f32_e32 v8, 0x3fc90fda, v7
	v_fma_f32 v10, v7, s73, -v8
	v_fmac_f32_e32 v10, 0x33a22168, v7
	v_fmac_f32_e32 v10, 0x3fc90fda, v6
	v_lshrrev_b32_e32 v7, 30, v9
	v_add_f32_e32 v6, v8, v10
	v_add_u32_e32 v7, v16, v7
.LBB0_103:
	s_andn2_saveexec_b64 s[14:15], s[46:47]
	v_mul_f32_e64 v6, |v4|, s74
	v_rndne_f32_e32 v8, v6
	v_cvt_i32_f32_e32 v7, v8
	v_fma_f32 v6, v8, s75, |v4|
	v_fmac_f32_e32 v6, 0xb3a22168, v8
	v_fmac_f32_e32 v6, 0xa7c234c4, v8
	s_or_b64 exec, exec, s[14:15]
	v_add_u32_e32 v8, s49, v122
	v_ashrrev_i32_e32 v9, 31, v8
	v_lshl_add_u64 v[8:9], v[8:9], 2, s[20:21]
	v_mov_b32_e32 v8, v241
	v_mul_f32_e32 v9, v6, v6
	v_fmamk_f32 v11, v9, 0xb94c1982, v128
	v_fmamk_f32 v12, v9, 0x37d75334, v129
	v_fmaak_f32 v11, v9, v11, 0xbe2aaa9d
	v_fmaak_f32 v12, v9, v12, 0x3d2aabf7
	v_lshlrev_b32_e32 v10, 30, v7
	v_and_b32_e32 v7, 1, v7
	v_mul_f32_e32 v11, v9, v11
	v_fmaak_f32 v12, v9, v12, 0xbf000004
	v_fmac_f32_e32 v6, v6, v11
	v_fma_f32 v9, v9, v12, 1.0
	v_cmp_eq_u32_e32 vcc, 0, v7
	v_xor_b32_e32 v5, v5, v4
	v_and_b32_e32 v13, 0x80000000, v10
	v_cndmask_b32_e32 v7, v9, v6, vcc
	v_xor_b32_e32 v6, 0x80000000, v6
	v_cndmask_b32_e32 v6, v6, v9, vcc
	v_bitop3_b32 v6, v6, v10, s78 bitop3:0x78
	v_cmp_class_f32_e64 vcc, v4, s79
	v_xor_b32_e32 v5, v5, v7
	v_xor_b32_e32 v5, v5, v13
	v_cndmask_b32_e32 v4, v134, v6, vcc
	v_cndmask_b32_e32 v5, v134, v5, vcc
	global_store_dword v[2:3], v4, off offset:2048
	global_store_dword v[0:1], v5, off offset:2048
	v_cvt_f32_i32_e32 v6, v8
	v_mul_f32_e32 v4, v118, v6
	v_and_b32_e32 v5, 0x7fffffff, v4
	v_cmp_nlt_f32_e64 s[0:1], |v4|, s33
	s_and_saveexec_b64 s[14:15], s[0:1]
	s_xor_b64 s[46:47], exec, s[14:15]
	s_cbranch_execz .LBB0_107
	v_lshrrev_b32_e32 v6, 23, v5
	v_add_u32_e32 v6, 0xffffff88, v6
	v_cmp_lt_u32_e32 vcc, 63, v6
	s_nop 1
	v_cndmask_b32_e32 v7, 0, v132, vcc
	v_add_u32_e32 v6, v7, v6
	v_cmp_lt_u32_e64 s[14:15], 31, v6
	s_nop 1
	v_cndmask_b32_e64 v7, 0, v133, s[14:15]
	v_add_u32_e32 v6, v7, v6
	v_cmp_lt_u32_e64 s[16:17], 31, v6
	s_nop 1
	v_cndmask_b32_e64 v7, 0, v133, s[16:17]
	v_add_u32_e32 v20, v7, v6
	v_and_b32_e32 v6, 0x7fffff, v5
	v_or_b32_e32 v18, 0x800000, v6
	v_mad_u64_u32 v[6:7], s[0:1], v18, s38, 0
	v_mov_b32_e32 v100, v7
	v_mad_u64_u32 v[8:9], s[0:1], v18, s39, v[100:101]
	v_mov_b32_e32 v100, v9
	v_mad_u64_u32 v[10:11], s[0:1], v18, s68, v[100:101]
	v_mov_b32_e32 v100, v11
	v_mad_u64_u32 v[12:13], s[0:1], v18, s69, v[100:101]
	v_mov_b32_e32 v100, v13
	v_mad_u64_u32 v[14:15], s[0:1], v18, s70, v[100:101]
	v_mov_b32_e32 v100, v15
	v_mad_u64_u32 v[16:17], s[0:1], v18, s71, v[100:101]
	v_mov_b32_e32 v100, v17
	v_mad_u64_u32 v[18:19], s[0:1], v18, s72, v[100:101]
	v_cndmask_b32_e32 v7, v16, v12, vcc
	v_cndmask_b32_e32 v9, v18, v14, vcc
	v_cndmask_b32_e32 v13, v19, v16, vcc
	v_cndmask_b32_e64 v11, v9, v7, s[14:15]
	v_cndmask_b32_e64 v9, v13, v9, s[14:15]
	v_cndmask_b32_e32 v13, v14, v10, vcc
	v_cndmask_b32_e64 v7, v7, v13, s[14:15]
	v_cndmask_b32_e32 v8, v12, v8, vcc
	v_cndmask_b32_e64 v9, v9, v11, s[16:17]
	v_cndmask_b32_e64 v11, v11, v7, s[16:17]
	v_sub_u32_e32 v14, 32, v20
	v_cndmask_b32_e64 v12, v13, v8, s[14:15]
	v_alignbit_b32 v15, v9, v11, v14
	v_cmp_eq_u32_e64 s[18:19], 0, v20
	v_cndmask_b32_e64 v7, v7, v12, s[16:17]
	v_alignbit_b32 v13, v11, v7, v14
	v_cndmask_b32_e64 v9, v15, v9, s[18:19]
	v_cndmask_b32_e32 v6, v10, v6, vcc
	v_cndmask_b32_e64 v11, v13, v11, s[18:19]
	v_bfe_u32 v16, v9, 29, 1
	v_cndmask_b32_e64 v6, v8, v6, s[14:15]
	v_alignbit_b32 v13, v9, v11, 30
	v_sub_u32_e32 v17, 0, v16
	v_cndmask_b32_e64 v6, v12, v6, s[16:17]
	v_xor_b32_e32 v13, v13, v17
	v_alignbit_b32 v8, v7, v6, v14
	v_cndmask_b32_e64 v7, v8, v7, s[18:19]
	v_ffbh_u32_e32 v10, v13
	v_alignbit_b32 v8, v11, v7, 30
	v_min_u32_e32 v10, 32, v10
	v_alignbit_b32 v6, v7, v6, 30
	v_xor_b32_e32 v8, v8, v17
	v_sub_u32_e32 v11, 31, v10
	v_xor_b32_e32 v6, v6, v17
	v_alignbit_b32 v12, v13, v8, v11
	v_alignbit_b32 v6, v8, v6, v11
	v_alignbit_b32 v7, v12, v6, 9
	v_ffbh_u32_e32 v8, v7
	v_min_u32_e32 v8, 32, v8
	v_lshrrev_b32_e32 v15, 29, v9
	v_not_b32_e32 v11, v8
	v_alignbit_b32 v6, v7, v6, v11
	v_lshlrev_b32_e32 v7, 31, v15
	v_or_b32_e32 v11, 0x33000000, v7
	v_add_lshl_u32 v8, v8, v10, 23
	v_lshrrev_b32_e32 v6, 9, v6
	v_sub_u32_e32 v8, v11, v8
	v_or_b32_e32 v7, 0.5, v7
	v_lshlrev_b32_e32 v10, 23, v10
	v_or_b32_e32 v6, v8, v6
	v_lshrrev_b32_e32 v8, 9, v12
	v_sub_u32_e32 v7, v7, v10
	v_or_b32_e32 v7, v8, v7
	v_mul_f32_e32 v8, 0x3fc90fda, v7
	v_fma_f32 v10, v7, s73, -v8
	v_fmac_f32_e32 v10, 0x33a22168, v7
	v_fmac_f32_e32 v10, 0x3fc90fda, v6
	v_lshrrev_b32_e32 v7, 30, v9
	v_add_f32_e32 v6, v8, v10
	v_add_u32_e32 v7, v16, v7
.LBB0_107:
	s_andn2_saveexec_b64 s[14:15], s[46:47]
	v_mul_f32_e64 v6, |v4|, s74
	v_rndne_f32_e32 v8, v6
	v_cvt_i32_f32_e32 v7, v8
	v_fma_f32 v6, v8, s75, |v4|
	v_fmac_f32_e32 v6, 0xb3a22168, v8
	v_fmac_f32_e32 v6, 0xa7c234c4, v8
	s_or_b64 exec, exec, s[14:15]
	v_add_u32_e32 v8, s49, v123
	v_ashrrev_i32_e32 v9, 31, v8
	v_lshl_add_u64 v[8:9], v[8:9], 2, s[20:21]
	v_mov_b32_e32 v10, v242
	v_mul_f32_e32 v11, v6, v6
	v_add_co_u32_e32 v2, vcc, s80, v2
	v_fmamk_f32 v13, v11, 0xb94c1982, v128
	s_nop 0
	v_addc_co_u32_e32 v3, vcc, 0, v3, vcc
	v_fmamk_f32 v14, v11, 0x37d75334, v129
	v_add_co_u32_e32 v8, vcc, s80, v0
	v_fmaak_f32 v13, v11, v13, 0xbe2aaa9d
	v_fmaak_f32 v14, v11, v14, 0x3d2aabf7
	v_lshlrev_b32_e32 v12, 30, v7
	v_and_b32_e32 v7, 1, v7
	v_addc_co_u32_e32 v9, vcc, 0, v1, vcc
	v_mul_f32_e32 v13, v11, v13
	v_fmaak_f32 v14, v11, v14, 0xbf000004
	v_fmac_f32_e32 v6, v6, v13
	v_fma_f32 v11, v11, v14, 1.0
	v_cmp_eq_u32_e32 vcc, 0, v7
	v_xor_b32_e32 v5, v5, v4
	v_and_b32_e32 v15, 0x80000000, v12
	v_cndmask_b32_e32 v7, v11, v6, vcc
	v_xor_b32_e32 v6, 0x80000000, v6
	v_cndmask_b32_e32 v6, v6, v11, vcc
	v_bitop3_b32 v6, v6, v12, s78 bitop3:0x78
	v_cmp_class_f32_e64 vcc, v4, s79
	v_xor_b32_e32 v5, v5, v7
	v_xor_b32_e32 v5, v5, v15
	v_cndmask_b32_e32 v4, v134, v6, vcc
	v_cndmask_b32_e32 v5, v134, v5, vcc
	global_store_dword v[2:3], v4, off
	global_store_dword v[8:9], v5, off
	v_cvt_f32_i32_e32 v6, v10
	v_mul_f32_e32 v4, v118, v6
	v_and_b32_e32 v5, 0x7fffffff, v4
	v_cmp_nlt_f32_e64 s[0:1], |v4|, s33
	s_and_saveexec_b64 s[14:15], s[0:1]
	s_xor_b64 s[46:47], exec, s[14:15]
	s_cbranch_execz .LBB0_111
	v_lshrrev_b32_e32 v6, 23, v5
	v_add_u32_e32 v6, 0xffffff88, v6
	v_cmp_lt_u32_e32 vcc, 63, v6
	s_nop 1
	v_cndmask_b32_e32 v7, 0, v132, vcc
	v_add_u32_e32 v6, v7, v6
	v_cmp_lt_u32_e64 s[14:15], 31, v6
	s_nop 1
	v_cndmask_b32_e64 v7, 0, v133, s[14:15]
	v_add_u32_e32 v6, v7, v6
	v_cmp_lt_u32_e64 s[16:17], 31, v6
	s_nop 1
	v_cndmask_b32_e64 v7, 0, v133, s[16:17]
	v_add_u32_e32 v20, v7, v6
	v_and_b32_e32 v6, 0x7fffff, v5
	v_or_b32_e32 v18, 0x800000, v6
	v_mad_u64_u32 v[6:7], s[0:1], v18, s38, 0
	v_mov_b32_e32 v100, v7
	v_mad_u64_u32 v[8:9], s[0:1], v18, s39, v[100:101]
	v_mov_b32_e32 v100, v9
	v_mad_u64_u32 v[10:11], s[0:1], v18, s68, v[100:101]
	v_mov_b32_e32 v100, v11
	v_mad_u64_u32 v[12:13], s[0:1], v18, s69, v[100:101]
	v_mov_b32_e32 v100, v13
	v_mad_u64_u32 v[14:15], s[0:1], v18, s70, v[100:101]
	v_mov_b32_e32 v100, v15
	v_mad_u64_u32 v[16:17], s[0:1], v18, s71, v[100:101]
	v_mov_b32_e32 v100, v17
	v_mad_u64_u32 v[18:19], s[0:1], v18, s72, v[100:101]
	v_cndmask_b32_e32 v7, v16, v12, vcc
	v_cndmask_b32_e32 v9, v18, v14, vcc
	v_cndmask_b32_e32 v13, v19, v16, vcc
	v_cndmask_b32_e64 v11, v9, v7, s[14:15]
	v_cndmask_b32_e64 v9, v13, v9, s[14:15]
	v_cndmask_b32_e32 v13, v14, v10, vcc
	v_cndmask_b32_e64 v7, v7, v13, s[14:15]
	v_cndmask_b32_e32 v8, v12, v8, vcc
	v_cndmask_b32_e64 v9, v9, v11, s[16:17]
	v_cndmask_b32_e64 v11, v11, v7, s[16:17]
	v_sub_u32_e32 v14, 32, v20
	v_cndmask_b32_e64 v12, v13, v8, s[14:15]
	v_alignbit_b32 v15, v9, v11, v14
	v_cmp_eq_u32_e64 s[18:19], 0, v20
	v_cndmask_b32_e64 v7, v7, v12, s[16:17]
	v_alignbit_b32 v13, v11, v7, v14
	v_cndmask_b32_e64 v9, v15, v9, s[18:19]
	v_cndmask_b32_e32 v6, v10, v6, vcc
	v_cndmask_b32_e64 v11, v13, v11, s[18:19]
	v_bfe_u32 v16, v9, 29, 1
	v_cndmask_b32_e64 v6, v8, v6, s[14:15]
	v_alignbit_b32 v13, v9, v11, 30
	v_sub_u32_e32 v17, 0, v16
	v_cndmask_b32_e64 v6, v12, v6, s[16:17]
	v_xor_b32_e32 v13, v13, v17
	v_alignbit_b32 v8, v7, v6, v14
	v_cndmask_b32_e64 v7, v8, v7, s[18:19]
	v_ffbh_u32_e32 v10, v13
	v_alignbit_b32 v8, v11, v7, 30
	v_min_u32_e32 v10, 32, v10
	v_alignbit_b32 v6, v7, v6, 30
	v_xor_b32_e32 v8, v8, v17
	v_sub_u32_e32 v11, 31, v10
	v_xor_b32_e32 v6, v6, v17
	v_alignbit_b32 v12, v13, v8, v11
	v_alignbit_b32 v6, v8, v6, v11
	v_alignbit_b32 v7, v12, v6, 9
	v_ffbh_u32_e32 v8, v7
	v_min_u32_e32 v8, 32, v8
	v_lshrrev_b32_e32 v15, 29, v9
	v_not_b32_e32 v11, v8
	v_alignbit_b32 v6, v7, v6, v11
	v_lshlrev_b32_e32 v7, 31, v15
	v_or_b32_e32 v11, 0x33000000, v7
	v_add_lshl_u32 v8, v8, v10, 23
	v_lshrrev_b32_e32 v6, 9, v6
	v_sub_u32_e32 v8, v11, v8
	v_or_b32_e32 v7, 0.5, v7
	v_lshlrev_b32_e32 v10, 23, v10
	v_or_b32_e32 v6, v8, v6
	v_lshrrev_b32_e32 v8, 9, v12
	v_sub_u32_e32 v7, v7, v10
	v_or_b32_e32 v7, v8, v7
	v_mul_f32_e32 v8, 0x3fc90fda, v7
	v_fma_f32 v10, v7, s73, -v8
	v_fmac_f32_e32 v10, 0x33a22168, v7
	v_fmac_f32_e32 v10, 0x3fc90fda, v6
	v_lshrrev_b32_e32 v7, 30, v9
	v_add_f32_e32 v6, v8, v10
	v_add_u32_e32 v7, v16, v7

.LBB0_129:
	ds_read_b128 v[0:3], v124
	ds_read_b128 v[4:7], v124 offset:1024
	ds_read_b128 v[8:11], v124 offset:8192
	ds_read_b128 v[12:15], v124 offset:9216
	ds_read_b128 v[16:19], v124 offset:2048
	ds_read_b128 v[20:23], v124 offset:3072
	ds_read_b128 v[24:27], v124 offset:10240
	ds_read_b128 v[28:31], v124 offset:11264
	ds_read_b128 v[32:35], v124 offset:4096
	ds_read_b128 v[36:39], v124 offset:5120
	ds_read_b128 v[40:43], v124 offset:12288
	ds_read_b128 v[44:47], v124 offset:13312
	ds_read_b128 v[48:51], v124 offset:6144
	ds_read_b128 v[52:55], v124 offset:7168
	ds_read_b128 v[56:59], v124 offset:14336
	ds_read_b128 v[60:63], v124 offset:15360
	v_ashrrev_i32_e32 v111, 31, v110
	v_lshlrev_b64 v[64:65], 13, v[110:111]
	v_lshl_add_u64 v[114:115], v[108:109], 0, v[64:65]
	v_lshlrev_b64 v[64:65], 12, v[110:111]
	v_lshl_add_u64 v[116:117], v[112:113], 0, v[64:65]
	s_mov_b64 s[16:17], 0
	s_waitcnt vmcnt(0)
	v_mov_b64_e32 v[64:65], v[168:169]
	v_mov_b64_e32 v[66:67], v[170:171]
	v_mov_b64_e32 v[68:69], v[172:173]
	v_mov_b64_e32 v[70:71], v[174:175]
	v_mov_b64_e32 v[72:73], v[176:177]
	v_mov_b64_e32 v[74:75], v[178:179]
	v_mov_b64_e32 v[76:77], v[180:181]
	v_mov_b64_e32 v[78:79], v[182:183]
	v_mov_b64_e32 v[80:81], v[184:185]
	v_mov_b64_e32 v[82:83], v[186:187]
	v_mov_b64_e32 v[84:85], v[188:189]
	v_mov_b64_e32 v[86:87], v[190:191]
	v_mov_b64_e32 v[88:89], v[192:193]
	v_mov_b64_e32 v[90:91], v[194:195]
	v_mov_b64_e32 v[92:93], v[196:197]
	v_mov_b64_e32 v[94:95], v[198:199]
	global_load_dwordx4 v[172:175], v[232:233], off offset:-4096 nt
	global_load_dwordx4 v[168:171], v[232:233], off offset:-3072 nt
	global_load_dwordx4 v[176:179], v[232:233], off offset:-2048 nt
	global_load_dwordx4 v[180:183], v[232:233], off nt
	global_load_dwordx4 v[184:187], v[232:233], off offset:1024 nt
	global_load_dwordx4 v[188:191], v[232:233], off offset:-1024 nt
	global_load_dwordx4 v[192:195], v[232:233], off offset:3072 nt
	global_load_dwordx4 v[196:199], v[232:233], off offset:2048 nt
	v_lshl_add_u64 v[232:233], v[232:233], 0, s[22:23]
	v_lshl_add_u64 v[136:137], v[116:117], 0, s[16:17]
	v_add_co_u32_e32 v136, vcc, s84, v136
	s_add_u32 s16, s16, 0x1000
	s_nop 0
	v_addc_co_u32_e32 v137, vcc, 0, v137, vcc
	s_addc_u32 s17, s17, 0
	s_cmpk_eq_i32 s16, 0x4000
	v_mov_b32_e32 v140, v69
	v_mov_b32_e32 v141, v65
	v_mov_b32_e32 v144, v71
	v_mov_b32_e32 v145, v67
	v_mov_b32_e32 v138, v68
	v_mov_b32_e32 v139, v64
	v_mov_b32_e32 v142, v70
	v_mov_b32_e32 v143, v66
	v_pk_mul_f32 v[146:147], v[74:75], v[74:75]
	v_pk_mul_f32 v[148:149], v[72:73], v[72:73]
	v_pk_mul_f32 v[140:141], v[140:141], v[140:141]
	v_pk_mul_f32 v[144:145], v[144:145], v[144:145]
	v_pk_mov_b32 v[160:161], v[148:149], v[146:147] op_sel:[1,0]
	v_mov_b32_e32 v149, v147
	v_pk_fma_f32 v[138:139], v[138:139], v[138:139], v[140:141]
	v_pk_fma_f32 v[140:141], v[142:143], v[142:143], v[144:145]
	v_pk_mul_f32 v[150:151], v[82:83], v[82:83]
	v_pk_mul_f32 v[152:153], v[80:81], v[80:81]
	v_mul_f32_e32 v100, v85, v85
	v_mul_f32_e32 v154, v87, v87
	v_pk_add_f32 v[142:143], v[160:161], v[148:149]
	v_pk_add_f32 v[138:139], v[138:139], v[140:141]
	v_mul_f32_e32 v103, v76, v76
	v_mul_f32_e32 v111, v77, v77
	v_mul_f32_e32 v135, v78, v78
	v_mul_f32_e32 v162, v79, v79
	v_pk_mov_b32 v[146:147], v[152:153], v[150:151] op_sel:[1,0]
	v_mov_b32_e32 v153, v151
	v_pk_fma_f32 v[150:151], v[84:85], v[84:85], v[100:101] op_sel_hi:[1,1,0]
	v_pk_fma_f32 v[154:155], v[86:87], v[86:87], v[154:155] op_sel_hi:[1,1,0]
	v_pk_add_f32 v[140:141], v[142:143], v[142:143] op_sel:[0,1] op_sel_hi:[1,0]
	v_pk_add_f32 v[138:139], v[138:139], v[138:139] op_sel:[0,1] op_sel_hi:[1,0]
	v_mov_b32_e32 v151, v135
	v_mov_b32_e32 v155, v162
	v_mov_b32_e32 v141, v111
	v_mov_b32_e32 v139, v103
	v_pk_add_f32 v[142:143], v[150:151], v[154:155]
	v_pk_add_f32 v[138:139], v[138:139], v[140:141]
	v_mul_f32_e32 v156, v93, v93
	v_mul_f32_e32 v158, v95, v95
	v_pk_add_f32 v[144:145], v[146:147], v[152:153]
	v_pk_add_f32 v[138:139], v[138:139], v[142:143]
	v_mul_f32_e32 v163, v88, v88
	v_mul_f32_e32 v164, v89, v89
	v_mul_f32_e32 v165, v90, v90
	v_mul_f32_e32 v166, v91, v91
	v_pk_fma_f32 v[156:157], v[92:93], v[92:93], v[156:157] op_sel_hi:[1,1,0]
	v_pk_fma_f32 v[158:159], v[94:95], v[94:95], v[158:159] op_sel_hi:[1,1,0]
	v_pk_add_f32 v[144:145], v[144:145], v[144:145] op_sel:[0,1] op_sel_hi:[1,0]
	v_pk_add_f32 v[138:139], v[138:139], v[138:139] op_sel:[0,1] op_sel_hi:[1,0]
	v_mov_b32_e32 v157, v165
	v_mov_b32_e32 v159, v166
	v_mov_b32_e32 v145, v164
	v_mov_b32_e32 v139, v163
	v_pk_add_f32 v[146:147], v[156:157], v[158:159]
	v_pk_add_f32 v[138:139], v[138:139], v[144:145]
	s_nop 0
	v_pk_add_f32 v[138:139], v[138:139], v[146:147]
	s_nop 0
	v_add_f32_e32 v100, v138, v139
	ds_swizzle_b32 v103, v100 offset:swizzle(SWAP,1)
	s_waitcnt lgkmcnt(0)
	v_add_f32_e32 v100, v100, v103
	ds_swizzle_b32 v103, v100 offset:swizzle(SWAP,2)
	s_waitcnt lgkmcnt(0)
	v_add_f32_e32 v100, v100, v103
	ds_swizzle_b32 v103, v100 offset:swizzle(SWAP,4)
	s_waitcnt lgkmcnt(0)
	v_add_f32_e32 v100, v100, v103
	ds_swizzle_b32 v103, v100 offset:swizzle(SWAP,8)
	s_waitcnt lgkmcnt(0)
	v_add_f32_e32 v100, v100, v103
	ds_swizzle_b32 v103, v100 offset:swizzle(SWAP,16)
	s_waitcnt lgkmcnt(0)
	v_add_f32_e32 v100, v100, v103
	ds_bpermute_b32 v103, v119, v100
	s_waitcnt lgkmcnt(0)
	v_add_f32_e32 v100, v100, v103
	v_fmamk_f32 v100, v100, 0x3a000000, v130
	v_mul_f32_e32 v103, 0x4f800000, v100
	v_cmp_gt_f32_e32 vcc, s83, v100
	s_nop 1
	v_cndmask_b32_e32 v100, v100, v103, vcc
	v_sqrt_f32_e32 v103, v100
	s_nop 0
	v_add_u32_e32 v111, -1, v103
	v_add_u32_e32 v135, 1, v103
	v_fma_f32 v138, -v111, v103, v100
	v_fma_f32 v139, -v135, v103, v100
	v_cmp_ge_f32_e64 s[14:15], 0, v138
	s_nop 1
	v_cndmask_b32_e64 v103, v103, v111, s[14:15]
	v_cmp_lt_f32_e64 s[14:15], 0, v139
	s_nop 1
	v_cndmask_b32_e64 v103, v103, v135, s[14:15]
	v_mul_f32_e32 v111, 0x37800000, v103
	v_cndmask_b32_e32 v103, v103, v111, vcc
	v_cmp_class_f32_e32 vcc, v100, v131
	s_nop 1
	v_cndmask_b32_e32 v100, v103, v100, vcc
	v_div_scale_f32 v103, s[0:1], v100, v100, 1.0
	v_rcp_f32_e32 v135, v103
	v_div_scale_f32 v111, vcc, 1.0, v100, 1.0
	v_fma_f32 v138, -v103, v135, 1.0
	v_fmac_f32_e32 v135, v138, v135
	v_mul_f32_e32 v138, v111, v135
	v_fma_f32 v139, -v103, v138, v111
	v_fmac_f32_e32 v138, v139, v135
	v_fma_f32 v103, -v103, v138, v111
	v_div_fmas_f32 v103, v103, v135, v138
	v_div_fixup_f32 v100, v103, v100, 1.0
	v_pk_mul_f32 v[68:69], v[68:69], v[100:101] op_sel_hi:[1,0]
	v_pk_mul_f32 v[70:71], v[70:71], v[100:101] op_sel_hi:[1,0]
	v_pk_mul_f32 v[64:65], v[64:65], v[100:101] op_sel_hi:[1,0]
	v_pk_mul_f32 v[66:67], v[66:67], v[100:101] op_sel_hi:[1,0]
	v_pk_mul_f32 v[72:73], v[72:73], v[100:101] op_sel_hi:[1,0]
	v_pk_mul_f32 v[74:75], v[74:75], v[100:101] op_sel_hi:[1,0]
	v_pk_mul_f32 v[84:85], v[84:85], v[100:101] op_sel_hi:[1,0]
	v_pk_mul_f32 v[86:87], v[86:87], v[100:101] op_sel_hi:[1,0]
	v_pk_mul_f32 v[76:77], v[76:77], v[100:101] op_sel_hi:[1,0]
	v_pk_mul_f32 v[78:79], v[78:79], v[100:101] op_sel_hi:[1,0]
	v_pk_mul_f32 v[80:81], v[80:81], v[100:101] op_sel_hi:[1,0]
	v_pk_mul_f32 v[82:83], v[82:83], v[100:101] op_sel_hi:[1,0]
	v_pk_mul_f32 v[92:93], v[92:93], v[100:101] op_sel_hi:[1,0]
	v_pk_mul_f32 v[94:95], v[94:95], v[100:101] op_sel_hi:[1,0]
	v_pk_mul_f32 v[88:89], v[88:89], v[100:101] op_sel_hi:[1,0]
	v_pk_mul_f32 v[90:91], v[90:91], v[100:101] op_sel_hi:[1,0]
	v_pk_fma_f32 v[70:71], v[2:3], v[70:71], v[10:11]
	v_pk_fma_f32 v[68:69], v[0:1], v[68:69], v[8:9]
	v_pk_fma_f32 v[66:67], v[6:7], v[66:67], v[14:15]
	v_pk_fma_f32 v[64:65], v[4:5], v[64:65], v[12:13]
	v_pk_fma_f32 v[74:75], v[18:19], v[74:75], v[26:27]
	v_pk_fma_f32 v[72:73], v[16:17], v[72:73], v[24:25]
	v_pk_fma_f32 v[86:87], v[22:23], v[86:87], v[30:31]
	v_pk_fma_f32 v[84:85], v[20:21], v[84:85], v[28:29]
	v_pk_fma_f32 v[78:79], v[78:79], v[34:35], v[42:43]
	v_pk_fma_f32 v[76:77], v[76:77], v[32:33], v[40:41]
	v_pk_fma_f32 v[82:83], v[82:83], v[38:39], v[46:47]
	v_pk_fma_f32 v[80:81], v[80:81], v[36:37], v[44:45]
	v_pk_fma_f32 v[94:95], v[94:95], v[50:51], v[58:59]
	v_pk_fma_f32 v[92:93], v[92:93], v[48:49], v[56:57]
	v_pk_fma_f32 v[90:91], v[90:91], v[54:55], v[62:63]
	v_pk_fma_f32 v[88:89], v[88:89], v[52:53], v[60:61]
	v_cvt_pk_bf16_f32 v68, v68, v69
	v_cvt_pk_bf16_f32 v69, v70, v71
	v_cvt_pk_bf16_f32 v64, v64, v65
	v_cvt_pk_bf16_f32 v65, v66, v67
	v_cvt_pk_bf16_f32 v66, v72, v73
	v_cvt_pk_bf16_f32 v67, v74, v75
	v_cvt_pk_bf16_f32 v70, v84, v85
	v_cvt_pk_bf16_f32 v71, v86, v87
	v_cvt_pk_bf16_f32 v72, v76, v77
	v_cvt_pk_bf16_f32 v73, v78, v79
	v_cvt_pk_bf16_f32 v74, v80, v81
	v_cvt_pk_bf16_f32 v75, v82, v83
	v_cvt_pk_bf16_f32 v76, v92, v93
	v_cvt_pk_bf16_f32 v77, v94, v95
	v_cvt_pk_bf16_f32 v78, v88, v89
	v_cvt_pk_bf16_f32 v79, v90, v91
	global_store_dwordx2 v[136:137], v[68:69], off
	global_store_dwordx2 v[136:137], v[64:65], off offset:512
	global_store_dwordx2 v[136:137], v[66:67], off offset:1024
	global_store_dwordx2 v[136:137], v[70:71], off offset:1536
	global_store_dwordx2 v[136:137], v[72:73], off offset:2048
	global_store_dwordx2 v[136:137], v[74:75], off offset:2560
	global_store_dwordx2 v[136:137], v[76:77], off offset:3072
	global_store_dwordx2 v[136:137], v[78:79], off offset:3584
	v_mov_b64_e32 v[64:65], v[200:201]
	v_mov_b64_e32 v[66:67], v[202:203]
	v_mov_b64_e32 v[68:69], v[204:205]
	v_mov_b64_e32 v[70:71], v[206:207]
	v_mov_b64_e32 v[72:73], v[208:209]
	v_mov_b64_e32 v[74:75], v[210:211]
	v_mov_b64_e32 v[76:77], v[212:213]
	v_mov_b64_e32 v[78:79], v[214:215]
	v_mov_b64_e32 v[80:81], v[216:217]
	v_mov_b64_e32 v[82:83], v[218:219]
	v_mov_b64_e32 v[84:85], v[220:221]
	v_mov_b64_e32 v[86:87], v[222:223]
	v_mov_b64_e32 v[88:89], v[224:225]
	v_mov_b64_e32 v[90:91], v[226:227]
	v_mov_b64_e32 v[92:93], v[228:229]
	v_mov_b64_e32 v[94:95], v[230:231]
	global_load_dwordx4 v[204:207], v[232:233], off offset:-4096 nt
	global_load_dwordx4 v[200:203], v[232:233], off offset:-3072 nt
	global_load_dwordx4 v[208:211], v[232:233], off offset:-2048 nt
	global_load_dwordx4 v[212:215], v[232:233], off nt
	global_load_dwordx4 v[216:219], v[232:233], off offset:1024 nt
	global_load_dwordx4 v[220:223], v[232:233], off offset:-1024 nt
	global_load_dwordx4 v[224:227], v[232:233], off offset:3072 nt
	global_load_dwordx4 v[228:231], v[232:233], off offset:2048 nt
	v_lshl_add_u64 v[232:233], v[232:233], 0, s[22:23]
	v_lshl_add_u64 v[136:137], v[116:117], 0, s[16:17]
	v_add_co_u32_e32 v136, vcc, s84, v136
	s_add_u32 s16, s16, 0x1000
	s_nop 0
	v_addc_co_u32_e32 v137, vcc, 0, v137, vcc
	s_addc_u32 s17, s17, 0
	s_cmpk_eq_i32 s16, 0x4000
	v_mov_b32_e32 v140, v69
	v_mov_b32_e32 v141, v65
	v_mov_b32_e32 v144, v71
	v_mov_b32_e32 v145, v67
	v_mov_b32_e32 v138, v68
	v_mov_b32_e32 v139, v64
	v_mov_b32_e32 v142, v70
	v_mov_b32_e32 v143, v66
	v_pk_mul_f32 v[146:147], v[74:75], v[74:75]
	v_pk_mul_f32 v[148:149], v[72:73], v[72:73]
	v_pk_mul_f32 v[140:141], v[140:141], v[140:141]
	v_pk_mul_f32 v[144:145], v[144:145], v[144:145]
	v_pk_mov_b32 v[160:161], v[148:149], v[146:147] op_sel:[1,0]
	v_mov_b32_e32 v149, v147
	v_pk_fma_f32 v[138:139], v[138:139], v[138:139], v[140:141]
	v_pk_fma_f32 v[140:141], v[142:143], v[142:143], v[144:145]
	v_pk_mul_f32 v[150:151], v[82:83], v[82:83]
	v_pk_mul_f32 v[152:153], v[80:81], v[80:81]
	v_mul_f32_e32 v100, v85, v85
	v_mul_f32_e32 v154, v87, v87
	v_pk_add_f32 v[142:143], v[160:161], v[148:149]
	v_pk_add_f32 v[138:139], v[138:139], v[140:141]
	v_mul_f32_e32 v103, v76, v76
	v_mul_f32_e32 v111, v77, v77
	v_mul_f32_e32 v135, v78, v78
	v_mul_f32_e32 v162, v79, v79
	v_pk_mov_b32 v[146:147], v[152:153], v[150:151] op_sel:[1,0]
	v_mov_b32_e32 v153, v151
	v_pk_fma_f32 v[150:151], v[84:85], v[84:85], v[100:101] op_sel_hi:[1,1,0]
	v_pk_fma_f32 v[154:155], v[86:87], v[86:87], v[154:155] op_sel_hi:[1,1,0]
	v_pk_add_f32 v[140:141], v[142:143], v[142:143] op_sel:[0,1] op_sel_hi:[1,0]
	v_pk_add_f32 v[138:139], v[138:139], v[138:139] op_sel:[0,1] op_sel_hi:[1,0]
	v_mov_b32_e32 v151, v135
	v_mov_b32_e32 v155, v162
	v_mov_b32_e32 v141, v111
	v_mov_b32_e32 v139, v103
	v_pk_add_f32 v[142:143], v[150:151], v[154:155]
	v_pk_add_f32 v[138:139], v[138:139], v[140:141]
	v_mul_f32_e32 v156, v93, v93
	v_mul_f32_e32 v158, v95, v95
	v_pk_add_f32 v[144:145], v[146:147], v[152:153]
	v_pk_add_f32 v[138:139], v[138:139], v[142:143]
	v_mul_f32_e32 v163, v88, v88
	v_mul_f32_e32 v164, v89, v89
	v_mul_f32_e32 v165, v90, v90
	v_mul_f32_e32 v166, v91, v91
	v_pk_fma_f32 v[156:157], v[92:93], v[92:93], v[156:157] op_sel_hi:[1,1,0]
	v_pk_fma_f32 v[158:159], v[94:95], v[94:95], v[158:159] op_sel_hi:[1,1,0]
	v_pk_add_f32 v[144:145], v[144:145], v[144:145] op_sel:[0,1] op_sel_hi:[1,0]
	v_pk_add_f32 v[138:139], v[138:139], v[138:139] op_sel:[0,1] op_sel_hi:[1,0]
	v_mov_b32_e32 v157, v165
	v_mov_b32_e32 v159, v166
	v_mov_b32_e32 v145, v164
	v_mov_b32_e32 v139, v163
	v_pk_add_f32 v[146:147], v[156:157], v[158:159]
	v_pk_add_f32 v[138:139], v[138:139], v[144:145]
	s_nop 0
	v_pk_add_f32 v[138:139], v[138:139], v[146:147]
	s_nop 0
	v_add_f32_e32 v100, v138, v139
	ds_swizzle_b32 v103, v100 offset:swizzle(SWAP,1)
	s_waitcnt lgkmcnt(0)
	v_add_f32_e32 v100, v100, v103
	ds_swizzle_b32 v103, v100 offset:swizzle(SWAP,2)
	s_waitcnt lgkmcnt(0)
	v_add_f32_e32 v100, v100, v103
	ds_swizzle_b32 v103, v100 offset:swizzle(SWAP,4)
	s_waitcnt lgkmcnt(0)
	v_add_f32_e32 v100, v100, v103
	ds_swizzle_b32 v103, v100 offset:swizzle(SWAP,8)
	s_waitcnt lgkmcnt(0)
	v_add_f32_e32 v100, v100, v103
	ds_swizzle_b32 v103, v100 offset:swizzle(SWAP,16)
	s_waitcnt lgkmcnt(0)
	v_add_f32_e32 v100, v100, v103
	ds_bpermute_b32 v103, v119, v100
	s_waitcnt lgkmcnt(0)
	v_add_f32_e32 v100, v100, v103
	v_fmamk_f32 v100, v100, 0x3a000000, v130
	v_mul_f32_e32 v103, 0x4f800000, v100
	v_cmp_gt_f32_e32 vcc, s83, v100
	s_nop 1
	v_cndmask_b32_e32 v100, v100, v103, vcc
	v_sqrt_f32_e32 v103, v100
	s_nop 0
	v_add_u32_e32 v111, -1, v103
	v_add_u32_e32 v135, 1, v103
	v_fma_f32 v138, -v111, v103, v100
	v_fma_f32 v139, -v135, v103, v100
	v_cmp_ge_f32_e64 s[14:15], 0, v138
	s_nop 1
	v_cndmask_b32_e64 v103, v103, v111, s[14:15]
	v_cmp_lt_f32_e64 s[14:15], 0, v139
	s_nop 1
	v_cndmask_b32_e64 v103, v103, v135, s[14:15]
	v_mul_f32_e32 v111, 0x37800000, v103
	v_cndmask_b32_e32 v103, v103, v111, vcc
	v_cmp_class_f32_e32 vcc, v100, v131
	s_nop 1
	v_cndmask_b32_e32 v100, v103, v100, vcc
	v_div_scale_f32 v103, s[0:1], v100, v100, 1.0
	v_rcp_f32_e32 v135, v103
	v_div_scale_f32 v111, vcc, 1.0, v100, 1.0
	v_fma_f32 v138, -v103, v135, 1.0
	v_fmac_f32_e32 v135, v138, v135
	v_mul_f32_e32 v138, v111, v135
	v_fma_f32 v139, -v103, v138, v111
	v_fmac_f32_e32 v138, v139, v135
	v_fma_f32 v103, -v103, v138, v111
	v_div_fmas_f32 v103, v103, v135, v138
	v_div_fixup_f32 v100, v103, v100, 1.0
	v_pk_mul_f32 v[68:69], v[68:69], v[100:101] op_sel_hi:[1,0]
	v_pk_mul_f32 v[70:71], v[70:71], v[100:101] op_sel_hi:[1,0]
	v_pk_mul_f32 v[64:65], v[64:65], v[100:101] op_sel_hi:[1,0]
	v_pk_mul_f32 v[66:67], v[66:67], v[100:101] op_sel_hi:[1,0]
	v_pk_mul_f32 v[72:73], v[72:73], v[100:101] op_sel_hi:[1,0]
	v_pk_mul_f32 v[74:75], v[74:75], v[100:101] op_sel_hi:[1,0]
	v_pk_mul_f32 v[84:85], v[84:85], v[100:101] op_sel_hi:[1,0]
	v_pk_mul_f32 v[86:87], v[86:87], v[100:101] op_sel_hi:[1,0]
	v_pk_mul_f32 v[76:77], v[76:77], v[100:101] op_sel_hi:[1,0]
	v_pk_mul_f32 v[78:79], v[78:79], v[100:101] op_sel_hi:[1,0]
	v_pk_mul_f32 v[80:81], v[80:81], v[100:101] op_sel_hi:[1,0]
	v_pk_mul_f32 v[82:83], v[82:83], v[100:101] op_sel_hi:[1,0]
	v_pk_mul_f32 v[92:93], v[92:93], v[100:101] op_sel_hi:[1,0]
	v_pk_mul_f32 v[94:95], v[94:95], v[100:101] op_sel_hi:[1,0]
	v_pk_mul_f32 v[88:89], v[88:89], v[100:101] op_sel_hi:[1,0]
	v_pk_mul_f32 v[90:91], v[90:91], v[100:101] op_sel_hi:[1,0]
	v_pk_fma_f32 v[70:71], v[2:3], v[70:71], v[10:11]
	v_pk_fma_f32 v[68:69], v[0:1], v[68:69], v[8:9]
	v_pk_fma_f32 v[66:67], v[6:7], v[66:67], v[14:15]
	v_pk_fma_f32 v[64:65], v[4:5], v[64:65], v[12:13]
	v_pk_fma_f32 v[74:75], v[18:19], v[74:75], v[26:27]
	v_pk_fma_f32 v[72:73], v[16:17], v[72:73], v[24:25]
	v_pk_fma_f32 v[86:87], v[22:23], v[86:87], v[30:31]
	v_pk_fma_f32 v[84:85], v[20:21], v[84:85], v[28:29]
	v_pk_fma_f32 v[78:79], v[78:79], v[34:35], v[42:43]
	v_pk_fma_f32 v[76:77], v[76:77], v[32:33], v[40:41]
	v_pk_fma_f32 v[82:83], v[82:83], v[38:39], v[46:47]
	v_pk_fma_f32 v[80:81], v[80:81], v[36:37], v[44:45]
	v_pk_fma_f32 v[94:95], v[94:95], v[50:51], v[58:59]
	v_pk_fma_f32 v[92:93], v[92:93], v[48:49], v[56:57]
	v_pk_fma_f32 v[90:91], v[90:91], v[54:55], v[62:63]
	v_pk_fma_f32 v[88:89], v[88:89], v[52:53], v[60:61]
	v_cvt_pk_bf16_f32 v68, v68, v69
	v_cvt_pk_bf16_f32 v69, v70, v71
	v_cvt_pk_bf16_f32 v64, v64, v65
	v_cvt_pk_bf16_f32 v65, v66, v67
	v_cvt_pk_bf16_f32 v66, v72, v73
	v_cvt_pk_bf16_f32 v67, v74, v75
	v_cvt_pk_bf16_f32 v70, v84, v85
	v_cvt_pk_bf16_f32 v71, v86, v87
	v_cvt_pk_bf16_f32 v72, v76, v77
	v_cvt_pk_bf16_f32 v73, v78, v79
	v_cvt_pk_bf16_f32 v74, v80, v81
	v_cvt_pk_bf16_f32 v75, v82, v83
	v_cvt_pk_bf16_f32 v76, v92, v93
	v_cvt_pk_bf16_f32 v77, v94, v95
	v_cvt_pk_bf16_f32 v78, v88, v89
	v_cvt_pk_bf16_f32 v79, v90, v91
	global_store_dwordx2 v[136:137], v[68:69], off
	global_store_dwordx2 v[136:137], v[64:65], off offset:512
	global_store_dwordx2 v[136:137], v[66:67], off offset:1024
	global_store_dwordx2 v[136:137], v[70:71], off offset:1536
	global_store_dwordx2 v[136:137], v[72:73], off offset:2048
	global_store_dwordx2 v[136:137], v[74:75], off offset:2560
	global_store_dwordx2 v[136:137], v[76:77], off offset:3072
	global_store_dwordx2 v[136:137], v[78:79], off offset:3584
	s_waitcnt vmcnt(24)
	v_mov_b64_e32 v[64:65], v[168:169]
	v_mov_b64_e32 v[66:67], v[170:171]
	v_mov_b64_e32 v[68:69], v[172:173]
	v_mov_b64_e32 v[70:71], v[174:175]
	v_mov_b64_e32 v[72:73], v[176:177]
	v_mov_b64_e32 v[74:75], v[178:179]
	v_mov_b64_e32 v[76:77], v[180:181]
	v_mov_b64_e32 v[78:79], v[182:183]
	v_mov_b64_e32 v[80:81], v[184:185]
	v_mov_b64_e32 v[82:83], v[186:187]
	v_mov_b64_e32 v[84:85], v[188:189]
	v_mov_b64_e32 v[86:87], v[190:191]
	v_mov_b64_e32 v[88:89], v[192:193]
	v_mov_b64_e32 v[90:91], v[194:195]
	v_mov_b64_e32 v[92:93], v[196:197]
	v_mov_b64_e32 v[94:95], v[198:199]
	v_lshl_add_u64 v[136:137], v[116:117], 0, s[16:17]
	v_add_co_u32_e32 v136, vcc, s84, v136
	s_add_u32 s16, s16, 0x1000
	s_nop 0
	v_addc_co_u32_e32 v137, vcc, 0, v137, vcc
	s_addc_u32 s17, s17, 0
	s_cmpk_eq_i32 s16, 0x4000
	v_mov_b32_e32 v140, v69
	v_mov_b32_e32 v141, v65
	v_mov_b32_e32 v144, v71
	v_mov_b32_e32 v145, v67
	v_mov_b32_e32 v138, v68
	v_mov_b32_e32 v139, v64
	v_mov_b32_e32 v142, v70
	v_mov_b32_e32 v143, v66
	v_pk_mul_f32 v[146:147], v[74:75], v[74:75]
	v_pk_mul_f32 v[148:149], v[72:73], v[72:73]
	v_pk_mul_f32 v[140:141], v[140:141], v[140:141]
	v_pk_mul_f32 v[144:145], v[144:145], v[144:145]
	v_pk_mov_b32 v[160:161], v[148:149], v[146:147] op_sel:[1,0]
	v_mov_b32_e32 v149, v147
	v_pk_fma_f32 v[138:139], v[138:139], v[138:139], v[140:141]
	v_pk_fma_f32 v[140:141], v[142:143], v[142:143], v[144:145]
	v_pk_mul_f32 v[150:151], v[82:83], v[82:83]
	v_pk_mul_f32 v[152:153], v[80:81], v[80:81]
	v_mul_f32_e32 v100, v85, v85
	v_mul_f32_e32 v154, v87, v87
	v_pk_add_f32 v[142:143], v[160:161], v[148:149]
	v_pk_add_f32 v[138:139], v[138:139], v[140:141]
	v_mul_f32_e32 v103, v76, v76
	v_mul_f32_e32 v111, v77, v77
	v_mul_f32_e32 v135, v78, v78
	v_mul_f32_e32 v162, v79, v79
	v_pk_mov_b32 v[146:147], v[152:153], v[150:151] op_sel:[1,0]
	v_mov_b32_e32 v153, v151
	v_pk_fma_f32 v[150:151], v[84:85], v[84:85], v[100:101] op_sel_hi:[1,1,0]
	v_pk_fma_f32 v[154:155], v[86:87], v[86:87], v[154:155] op_sel_hi:[1,1,0]
	v_pk_add_f32 v[140:141], v[142:143], v[142:143] op_sel:[0,1] op_sel_hi:[1,0]
	v_pk_add_f32 v[138:139], v[138:139], v[138:139] op_sel:[0,1] op_sel_hi:[1,0]
	v_mov_b32_e32 v151, v135
	v_mov_b32_e32 v155, v162
	v_mov_b32_e32 v141, v111
	v_mov_b32_e32 v139, v103
	v_pk_add_f32 v[142:143], v[150:151], v[154:155]
	v_pk_add_f32 v[138:139], v[138:139], v[140:141]
	v_mul_f32_e32 v156, v93, v93
	v_mul_f32_e32 v158, v95, v95
	v_pk_add_f32 v[144:145], v[146:147], v[152:153]
	v_pk_add_f32 v[138:139], v[138:139], v[142:143]
	v_mul_f32_e32 v163, v88, v88
	v_mul_f32_e32 v164, v89, v89
	v_mul_f32_e32 v165, v90, v90
	v_mul_f32_e32 v166, v91, v91
	v_pk_fma_f32 v[156:157], v[92:93], v[92:93], v[156:157] op_sel_hi:[1,1,0]
	v_pk_fma_f32 v[158:159], v[94:95], v[94:95], v[158:159] op_sel_hi:[1,1,0]
	v_pk_add_f32 v[144:145], v[144:145], v[144:145] op_sel:[0,1] op_sel_hi:[1,0]
	v_pk_add_f32 v[138:139], v[138:139], v[138:139] op_sel:[0,1] op_sel_hi:[1,0]
	v_mov_b32_e32 v157, v165
	v_mov_b32_e32 v159, v166
	v_mov_b32_e32 v145, v164
	v_mov_b32_e32 v139, v163
	v_pk_add_f32 v[146:147], v[156:157], v[158:159]
	v_pk_add_f32 v[138:139], v[138:139], v[144:145]
	s_nop 0
	v_pk_add_f32 v[138:139], v[138:139], v[146:147]
	s_nop 0
	v_add_f32_e32 v100, v138, v139
	ds_swizzle_b32 v103, v100 offset:swizzle(SWAP,1)
	s_waitcnt lgkmcnt(0)
	v_add_f32_e32 v100, v100, v103
	ds_swizzle_b32 v103, v100 offset:swizzle(SWAP,2)
	s_waitcnt lgkmcnt(0)
	v_add_f32_e32 v100, v100, v103
	ds_swizzle_b32 v103, v100 offset:swizzle(SWAP,4)
	s_waitcnt lgkmcnt(0)
	v_add_f32_e32 v100, v100, v103
	ds_swizzle_b32 v103, v100 offset:swizzle(SWAP,8)
	s_waitcnt lgkmcnt(0)
	v_add_f32_e32 v100, v100, v103
	ds_swizzle_b32 v103, v100 offset:swizzle(SWAP,16)
	s_waitcnt lgkmcnt(0)
	v_add_f32_e32 v100, v100, v103
	ds_bpermute_b32 v103, v119, v100
	s_waitcnt lgkmcnt(0)
	v_add_f32_e32 v100, v100, v103
	v_fmamk_f32 v100, v100, 0x3a000000, v130
	v_mul_f32_e32 v103, 0x4f800000, v100
	v_cmp_gt_f32_e32 vcc, s83, v100
	s_nop 1
	v_cndmask_b32_e32 v100, v100, v103, vcc
	v_sqrt_f32_e32 v103, v100
	s_nop 0
	v_add_u32_e32 v111, -1, v103
	v_add_u32_e32 v135, 1, v103
	v_fma_f32 v138, -v111, v103, v100
	v_fma_f32 v139, -v135, v103, v100
	v_cmp_ge_f32_e64 s[14:15], 0, v138
	s_nop 1
	v_cndmask_b32_e64 v103, v103, v111, s[14:15]
	v_cmp_lt_f32_e64 s[14:15], 0, v139
	s_nop 1
	v_cndmask_b32_e64 v103, v103, v135, s[14:15]
	v_mul_f32_e32 v111, 0x37800000, v103
	v_cndmask_b32_e32 v103, v103, v111, vcc
	v_cmp_class_f32_e32 vcc, v100, v131
	s_nop 1
	v_cndmask_b32_e32 v100, v103, v100, vcc
	v_div_scale_f32 v103, s[0:1], v100, v100, 1.0
	v_rcp_f32_e32 v135, v103
	v_div_scale_f32 v111, vcc, 1.0, v100, 1.0
	v_fma_f32 v138, -v103, v135, 1.0
	v_fmac_f32_e32 v135, v138, v135
	v_mul_f32_e32 v138, v111, v135
	v_fma_f32 v139, -v103, v138, v111
	v_fmac_f32_e32 v138, v139, v135
	v_fma_f32 v103, -v103, v138, v111
	v_div_fmas_f32 v103, v103, v135, v138
	v_div_fixup_f32 v100, v103, v100, 1.0
	v_pk_mul_f32 v[68:69], v[68:69], v[100:101] op_sel_hi:[1,0]
	v_pk_mul_f32 v[70:71], v[70:71], v[100:101] op_sel_hi:[1,0]
	v_pk_mul_f32 v[64:65], v[64:65], v[100:101] op_sel_hi:[1,0]
	v_pk_mul_f32 v[66:67], v[66:67], v[100:101] op_sel_hi:[1,0]
	v_pk_mul_f32 v[72:73], v[72:73], v[100:101] op_sel_hi:[1,0]
	v_pk_mul_f32 v[74:75], v[74:75], v[100:101] op_sel_hi:[1,0]
	v_pk_mul_f32 v[84:85], v[84:85], v[100:101] op_sel_hi:[1,0]
	v_pk_mul_f32 v[86:87], v[86:87], v[100:101] op_sel_hi:[1,0]
	v_pk_mul_f32 v[76:77], v[76:77], v[100:101] op_sel_hi:[1,0]
	v_pk_mul_f32 v[78:79], v[78:79], v[100:101] op_sel_hi:[1,0]
	v_pk_mul_f32 v[80:81], v[80:81], v[100:101] op_sel_hi:[1,0]
	v_pk_mul_f32 v[82:83], v[82:83], v[100:101] op_sel_hi:[1,0]
	v_pk_mul_f32 v[92:93], v[92:93], v[100:101] op_sel_hi:[1,0]
	v_pk_mul_f32 v[94:95], v[94:95], v[100:101] op_sel_hi:[1,0]
	v_pk_mul_f32 v[88:89], v[88:89], v[100:101] op_sel_hi:[1,0]
	v_pk_mul_f32 v[90:91], v[90:91], v[100:101] op_sel_hi:[1,0]
	v_pk_fma_f32 v[70:71], v[2:3], v[70:71], v[10:11]
	v_pk_fma_f32 v[68:69], v[0:1], v[68:69], v[8:9]
	v_pk_fma_f32 v[66:67], v[6:7], v[66:67], v[14:15]
	v_pk_fma_f32 v[64:65], v[4:5], v[64:65], v[12:13]
	v_pk_fma_f32 v[74:75], v[18:19], v[74:75], v[26:27]
	v_pk_fma_f32 v[72:73], v[16:17], v[72:73], v[24:25]
	v_pk_fma_f32 v[86:87], v[22:23], v[86:87], v[30:31]
	v_pk_fma_f32 v[84:85], v[20:21], v[84:85], v[28:29]
	v_pk_fma_f32 v[78:79], v[78:79], v[34:35], v[42:43]
	v_pk_fma_f32 v[76:77], v[76:77], v[32:33], v[40:41]
	v_pk_fma_f32 v[82:83], v[82:83], v[38:39], v[46:47]
	v_pk_fma_f32 v[80:81], v[80:81], v[36:37], v[44:45]
	v_pk_fma_f32 v[94:95], v[94:95], v[50:51], v[58:59]
	v_pk_fma_f32 v[92:93], v[92:93], v[48:49], v[56:57]
	v_pk_fma_f32 v[90:91], v[90:91], v[54:55], v[62:63]
	v_pk_fma_f32 v[88:89], v[88:89], v[52:53], v[60:61]
	v_cvt_pk_bf16_f32 v68, v68, v69
	v_cvt_pk_bf16_f32 v69, v70, v71
	v_cvt_pk_bf16_f32 v64, v64, v65
	v_cvt_pk_bf16_f32 v65, v66, v67
	v_cvt_pk_bf16_f32 v66, v72, v73
	v_cvt_pk_bf16_f32 v67, v74, v75
	v_cvt_pk_bf16_f32 v70, v84, v85
	v_cvt_pk_bf16_f32 v71, v86, v87
	v_cvt_pk_bf16_f32 v72, v76, v77
	v_cvt_pk_bf16_f32 v73, v78, v79
	v_cvt_pk_bf16_f32 v74, v80, v81
	v_cvt_pk_bf16_f32 v75, v82, v83
	v_cvt_pk_bf16_f32 v76, v92, v93
	v_cvt_pk_bf16_f32 v77, v94, v95
	v_cvt_pk_bf16_f32 v78, v88, v89
	v_cvt_pk_bf16_f32 v79, v90, v91
	global_store_dwordx2 v[136:137], v[68:69], off
	global_store_dwordx2 v[136:137], v[64:65], off offset:512
	global_store_dwordx2 v[136:137], v[66:67], off offset:1024
	global_store_dwordx2 v[136:137], v[70:71], off offset:1536
	global_store_dwordx2 v[136:137], v[72:73], off offset:2048
	global_store_dwordx2 v[136:137], v[74:75], off offset:2560
	global_store_dwordx2 v[136:137], v[76:77], off offset:3072
	global_store_dwordx2 v[136:137], v[78:79], off offset:3584
	s_waitcnt vmcnt(16)
	v_mov_b64_e32 v[64:65], v[200:201]
	v_mov_b64_e32 v[66:67], v[202:203]
	v_mov_b64_e32 v[68:69], v[204:205]
	v_mov_b64_e32 v[70:71], v[206:207]
	v_mov_b64_e32 v[72:73], v[208:209]
	v_mov_b64_e32 v[74:75], v[210:211]
	v_mov_b64_e32 v[76:77], v[212:213]
	v_mov_b64_e32 v[78:79], v[214:215]
	v_mov_b64_e32 v[80:81], v[216:217]
	v_mov_b64_e32 v[82:83], v[218:219]
	v_mov_b64_e32 v[84:85], v[220:221]
	v_mov_b64_e32 v[86:87], v[222:223]
	v_mov_b64_e32 v[88:89], v[224:225]
	v_mov_b64_e32 v[90:91], v[226:227]
	v_mov_b64_e32 v[92:93], v[228:229]
	v_mov_b64_e32 v[94:95], v[230:231]
	v_lshl_add_u64 v[136:137], v[116:117], 0, s[16:17]
	v_add_co_u32_e32 v136, vcc, s84, v136
	s_add_u32 s16, s16, 0x1000
	s_nop 0
	v_addc_co_u32_e32 v137, vcc, 0, v137, vcc
	s_addc_u32 s17, s17, 0
	s_cmpk_eq_i32 s16, 0x4000
	v_mov_b32_e32 v140, v69
	v_mov_b32_e32 v141, v65
	v_mov_b32_e32 v144, v71
	v_mov_b32_e32 v145, v67
	v_mov_b32_e32 v138, v68
	v_mov_b32_e32 v139, v64
	v_mov_b32_e32 v142, v70
	v_mov_b32_e32 v143, v66
	v_pk_mul_f32 v[146:147], v[74:75], v[74:75]
	v_pk_mul_f32 v[148:149], v[72:73], v[72:73]
	v_pk_mul_f32 v[140:141], v[140:141], v[140:141]
	v_pk_mul_f32 v[144:145], v[144:145], v[144:145]
	v_pk_mov_b32 v[160:161], v[148:149], v[146:147] op_sel:[1,0]
	v_mov_b32_e32 v149, v147
	v_pk_fma_f32 v[138:139], v[138:139], v[138:139], v[140:141]
	v_pk_fma_f32 v[140:141], v[142:143], v[142:143], v[144:145]
	v_pk_mul_f32 v[150:151], v[82:83], v[82:83]
	v_pk_mul_f32 v[152:153], v[80:81], v[80:81]
	v_mul_f32_e32 v100, v85, v85
	v_mul_f32_e32 v154, v87, v87
	v_pk_add_f32 v[142:143], v[160:161], v[148:149]
	v_pk_add_f32 v[138:139], v[138:139], v[140:141]
	v_mul_f32_e32 v103, v76, v76
	v_mul_f32_e32 v111, v77, v77
	v_mul_f32_e32 v135, v78, v78
	v_mul_f32_e32 v162, v79, v79
	v_pk_mov_b32 v[146:147], v[152:153], v[150:151] op_sel:[1,0]
	v_mov_b32_e32 v153, v151
	v_pk_fma_f32 v[150:151], v[84:85], v[84:85], v[100:101] op_sel_hi:[1,1,0]
	v_pk_fma_f32 v[154:155], v[86:87], v[86:87], v[154:155] op_sel_hi:[1,1,0]
	v_pk_add_f32 v[140:141], v[142:143], v[142:143] op_sel:[0,1] op_sel_hi:[1,0]
	v_pk_add_f32 v[138:139], v[138:139], v[138:139] op_sel:[0,1] op_sel_hi:[1,0]
	v_mov_b32_e32 v151, v135
	v_mov_b32_e32 v155, v162
	v_mov_b32_e32 v141, v111
	v_mov_b32_e32 v139, v103
	v_pk_add_f32 v[142:143], v[150:151], v[154:155]
	v_pk_add_f32 v[138:139], v[138:139], v[140:141]
	v_mul_f32_e32 v156, v93, v93
	v_mul_f32_e32 v158, v95, v95
	v_pk_add_f32 v[144:145], v[146:147], v[152:153]
	v_pk_add_f32 v[138:139], v[138:139], v[142:143]
	v_mul_f32_e32 v163, v88, v88
	v_mul_f32_e32 v164, v89, v89
	v_mul_f32_e32 v165, v90, v90
	v_mul_f32_e32 v166, v91, v91
	v_pk_fma_f32 v[156:157], v[92:93], v[92:93], v[156:157] op_sel_hi:[1,1,0]
	v_pk_fma_f32 v[158:159], v[94:95], v[94:95], v[158:159] op_sel_hi:[1,1,0]
	v_pk_add_f32 v[144:145], v[144:145], v[144:145] op_sel:[0,1] op_sel_hi:[1,0]
	v_pk_add_f32 v[138:139], v[138:139], v[138:139] op_sel:[0,1] op_sel_hi:[1,0]
	v_mov_b32_e32 v157, v165
	v_mov_b32_e32 v159, v166
	v_mov_b32_e32 v145, v164
	v_mov_b32_e32 v139, v163
	v_pk_add_f32 v[146:147], v[156:157], v[158:159]
	v_pk_add_f32 v[138:139], v[138:139], v[144:145]
	s_nop 0
	v_pk_add_f32 v[138:139], v[138:139], v[146:147]
	s_nop 0
	v_add_f32_e32 v100, v138, v139
	ds_swizzle_b32 v103, v100 offset:swizzle(SWAP,1)
	s_waitcnt lgkmcnt(0)
	v_add_f32_e32 v100, v100, v103
	ds_swizzle_b32 v103, v100 offset:swizzle(SWAP,2)
	s_waitcnt lgkmcnt(0)
	v_add_f32_e32 v100, v100, v103
	ds_swizzle_b32 v103, v100 offset:swizzle(SWAP,4)
	s_waitcnt lgkmcnt(0)
	v_add_f32_e32 v100, v100, v103
	ds_swizzle_b32 v103, v100 offset:swizzle(SWAP,8)
	s_waitcnt lgkmcnt(0)
	v_add_f32_e32 v100, v100, v103
	ds_swizzle_b32 v103, v100 offset:swizzle(SWAP,16)
	s_waitcnt lgkmcnt(0)
	v_add_f32_e32 v100, v100, v103
	ds_bpermute_b32 v103, v119, v100
	s_waitcnt lgkmcnt(0)
	v_add_f32_e32 v100, v100, v103
	v_fmamk_f32 v100, v100, 0x3a000000, v130
	v_mul_f32_e32 v103, 0x4f800000, v100
	v_cmp_gt_f32_e32 vcc, s83, v100
	s_nop 1
	v_cndmask_b32_e32 v100, v100, v103, vcc
	v_sqrt_f32_e32 v103, v100
	s_nop 0
	v_add_u32_e32 v111, -1, v103
	v_add_u32_e32 v135, 1, v103
	v_fma_f32 v138, -v111, v103, v100
	v_fma_f32 v139, -v135, v103, v100
	v_cmp_ge_f32_e64 s[14:15], 0, v138
	s_nop 1
	v_cndmask_b32_e64 v103, v103, v111, s[14:15]
	v_cmp_lt_f32_e64 s[14:15], 0, v139
	s_nop 1
	v_cndmask_b32_e64 v103, v103, v135, s[14:15]
	v_mul_f32_e32 v111, 0x37800000, v103
	v_cndmask_b32_e32 v103, v103, v111, vcc
	v_cmp_class_f32_e32 vcc, v100, v131
	s_nop 1
	v_cndmask_b32_e32 v100, v103, v100, vcc
	v_div_scale_f32 v103, s[0:1], v100, v100, 1.0
	v_rcp_f32_e32 v135, v103
	v_div_scale_f32 v111, vcc, 1.0, v100, 1.0
	v_fma_f32 v138, -v103, v135, 1.0
	v_fmac_f32_e32 v135, v138, v135
	v_mul_f32_e32 v138, v111, v135
	v_fma_f32 v139, -v103, v138, v111
	v_fmac_f32_e32 v138, v139, v135
	v_fma_f32 v103, -v103, v138, v111
	v_div_fmas_f32 v103, v103, v135, v138
	v_div_fixup_f32 v100, v103, v100, 1.0
	v_pk_mul_f32 v[68:69], v[68:69], v[100:101] op_sel_hi:[1,0]
	v_pk_mul_f32 v[70:71], v[70:71], v[100:101] op_sel_hi:[1,0]
	v_pk_mul_f32 v[64:65], v[64:65], v[100:101] op_sel_hi:[1,0]
	v_pk_mul_f32 v[66:67], v[66:67], v[100:101] op_sel_hi:[1,0]
	v_pk_mul_f32 v[72:73], v[72:73], v[100:101] op_sel_hi:[1,0]
	v_pk_mul_f32 v[74:75], v[74:75], v[100:101] op_sel_hi:[1,0]
	v_pk_mul_f32 v[84:85], v[84:85], v[100:101] op_sel_hi:[1,0]
	v_pk_mul_f32 v[86:87], v[86:87], v[100:101] op_sel_hi:[1,0]
	v_pk_mul_f32 v[76:77], v[76:77], v[100:101] op_sel_hi:[1,0]
	v_pk_mul_f32 v[78:79], v[78:79], v[100:101] op_sel_hi:[1,0]
	v_pk_mul_f32 v[80:81], v[80:81], v[100:101] op_sel_hi:[1,0]
	v_pk_mul_f32 v[82:83], v[82:83], v[100:101] op_sel_hi:[1,0]
	v_pk_mul_f32 v[92:93], v[92:93], v[100:101] op_sel_hi:[1,0]
	v_pk_mul_f32 v[94:95], v[94:95], v[100:101] op_sel_hi:[1,0]
	v_pk_mul_f32 v[88:89], v[88:89], v[100:101] op_sel_hi:[1,0]
	v_pk_mul_f32 v[90:91], v[90:91], v[100:101] op_sel_hi:[1,0]
	v_pk_fma_f32 v[70:71], v[2:3], v[70:71], v[10:11]
	v_pk_fma_f32 v[68:69], v[0:1], v[68:69], v[8:9]
	v_pk_fma_f32 v[66:67], v[6:7], v[66:67], v[14:15]
	v_pk_fma_f32 v[64:65], v[4:5], v[64:65], v[12:13]
	v_pk_fma_f32 v[74:75], v[18:19], v[74:75], v[26:27]
	v_pk_fma_f32 v[72:73], v[16:17], v[72:73], v[24:25]
	v_pk_fma_f32 v[86:87], v[22:23], v[86:87], v[30:31]
	v_pk_fma_f32 v[84:85], v[20:21], v[84:85], v[28:29]
	v_pk_fma_f32 v[78:79], v[78:79], v[34:35], v[42:43]
	v_pk_fma_f32 v[76:77], v[76:77], v[32:33], v[40:41]
	v_pk_fma_f32 v[82:83], v[82:83], v[38:39], v[46:47]
	v_pk_fma_f32 v[80:81], v[80:81], v[36:37], v[44:45]
	v_pk_fma_f32 v[94:95], v[94:95], v[50:51], v[58:59]
	v_pk_fma_f32 v[92:93], v[92:93], v[48:49], v[56:57]
	v_pk_fma_f32 v[90:91], v[90:91], v[54:55], v[62:63]
	v_pk_fma_f32 v[88:89], v[88:89], v[52:53], v[60:61]
	v_cvt_pk_bf16_f32 v68, v68, v69
	v_cvt_pk_bf16_f32 v69, v70, v71
	v_cvt_pk_bf16_f32 v64, v64, v65
	v_cvt_pk_bf16_f32 v65, v66, v67
	v_cvt_pk_bf16_f32 v66, v72, v73
	v_cvt_pk_bf16_f32 v67, v74, v75
	v_cvt_pk_bf16_f32 v70, v84, v85
	v_cvt_pk_bf16_f32 v71, v86, v87
	v_cvt_pk_bf16_f32 v72, v76, v77
	v_cvt_pk_bf16_f32 v73, v78, v79
	v_cvt_pk_bf16_f32 v74, v80, v81
	v_cvt_pk_bf16_f32 v75, v82, v83
	v_cvt_pk_bf16_f32 v76, v92, v93
	v_cvt_pk_bf16_f32 v77, v94, v95
	v_cvt_pk_bf16_f32 v78, v88, v89
	v_cvt_pk_bf16_f32 v79, v90, v91
	global_store_dwordx2 v[136:137], v[68:69], off
	global_store_dwordx2 v[136:137], v[64:65], off offset:512
	global_store_dwordx2 v[136:137], v[66:67], off offset:1024
	global_store_dwordx2 v[136:137], v[70:71], off offset:1536
	global_store_dwordx2 v[136:137], v[72:73], off offset:2048
	global_store_dwordx2 v[136:137], v[74:75], off offset:2560
	global_store_dwordx2 v[136:137], v[76:77], off offset:3072
	global_store_dwordx2 v[136:137], v[78:79], off offset:3584
	s_add_i32 s42, s42, s34
	s_cmpk_gt_i32 s42, 0xff
	v_add_u32_e32 v110, s3, v110
	s_cbranch_scc0 .LBB0_97
